# GEMM tile headers without epilogue-store drains; RWKV stage without dead c1/c2 reductions; residual y loads without nt hint
# speedup vs baseline: 1.0329x; 1.0067x over previous
; __device__ __forceinline__ void unpack4(uint2 u, float* f) { f[0] = bflo(u.x); f[1] = bfhi(u.x); f[2] = bflo(u.y); f[3] = bfhi(u.y); }
; __device__ __forceinline__ void resid_norm(const float* hin, const u16* y, const float* gpost, const float* gpre, float* hout, u16* hn,
;                            int job0w, int jstridew) {
;     ...
;   for (int r0 = job0w * RN_R; r0 < T_TOK; r0 += jstridew * RN_R) {
;     uint2 yu[RN_R][4];
;     float4 h4[RN_R][4];
; #pragma unroll
;     for (int q = 0; q < RN_R; q++)
; #pragma unroll
;       for (int i = 0; i < 4; i++) {
;         { typedef unsigned u32x2_ __attribute__((ext_vector_type(2)));
;           const u32x2_ t_ = __builtin_nontemporal_load((const u32x2_*)(y + (size_t)(r0 + q) * 1024 + (lane + i * 64) * 4));
;           yu[q][i] = make_uint2(t_[0], t_[1]); }
;         {
;           const f32x4 t_ = __builtin_nontemporal_load((const f32x4*)(hin + (size_t)(r0 + q) * 1024) + lane + i * 64);
;           h4[q][i] = make_float4(t_[0], t_[1], t_[2], t_[3]); }
;       }
;     float4 gp[4];
; #pragma unroll
;     for (int i = 0; i < 4; i++) gp[i] = ((const float4*)gpost)[lane + i * 64];
; #pragma unroll
;     for (int q = 0; q < RN_R; q++) {
;       const int r = r0 + q;
;       float yv[16];
;       float ss = 0.f;
; #pragma unroll
;       for (int i = 0; i < 4; i++) {
;         unpack4(yu[q][i], yv + i * 4);
; #pragma unroll
;         for (int e = 0; e < 4; e++) ss += yv[i * 4 + e] * yv[i * 4 + e];
;       }
;       ss = wave_sum(ss);
.LBB0_88:
	global_load_dwordx2 v[50:51], v[12:13], off offset:-3584
	global_load_dwordx4 v[14:17], v[10:11], off offset:-4096 nt
	global_load_dwordx2 v[54:55], v[12:13], off offset:-3072
	global_load_dwordx4 v[18:21], v[10:11], off offset:-3072 nt
	global_load_dwordx2 v[58:59], v[12:13], off offset:-2560
	global_load_dwordx4 v[22:25], v[10:11], off offset:-2048 nt
	global_load_dwordx2 v[62:63], v[12:13], off offset:-2048
	global_load_dwordx4 v[26:29], v[10:11], off offset:-1024 nt
	global_load_dwordx2 v[64:65], v[12:13], off offset:-1536
	global_load_dwordx4 v[30:33], v[10:11], off nt
	global_load_dwordx2 v[66:67], v[12:13], off offset:-1024
	global_load_dwordx4 v[34:37], v[10:11], off offset:1024 nt
	global_load_dwordx2 v[68:69], v[12:13], off offset:-512
	global_load_dwordx4 v[38:41], v[10:11], off offset:2048 nt
	global_load_dwordx2 v[70:71], v[12:13], off
	global_load_dwordx4 v[42:45], v[10:11], off offset:3072 nt
	global_load_dwordx4 v[46:49], v[2:3], off
	v_add_u32_e32 v0, s16, v0
	v_lshl_add_u64 v[12:13], v[12:13], 0, s[14:15]
	s_waitcnt vmcnt(16)
	v_lshlrev_b32_e32 v72, 16, v50
	v_and_b32_e32 v73, 0xffff0000, v50
	v_lshlrev_b32_e32 v76, 16, v51
	v_and_b32_e32 v77, 0xffff0000, v51
	global_load_dwordx4 v[50:53], v[4:5], off
	s_waitcnt vmcnt(15)
	v_lshlrev_b32_e32 v80, 16, v54
	v_and_b32_e32 v81, 0xffff0000, v54
	v_lshlrev_b32_e32 v84, 16, v55
	v_and_b32_e32 v85, 0xffff0000, v55
	global_load_dwordx4 v[54:57], v[6:7], off
	s_waitcnt vmcnt(14)
	v_lshlrev_b32_e32 v88, 16, v58
	v_and_b32_e32 v89, 0xffff0000, v58
	v_lshlrev_b32_e32 v92, 16, v59
	v_and_b32_e32 v93, 0xffff0000, v59
	global_load_dwordx4 v[58:61], v[8:9], off
	v_pk_mul_f32 v[74:75], v[72:73], v[72:73]
	v_pk_mul_f32 v[78:79], v[76:77], v[76:77]
	v_add_f32_e32 v1, v74, v75
	v_add_f32_e32 v1, v78, v1
	v_pk_mul_f32 v[82:83], v[80:81], v[80:81]
	v_add_f32_e32 v1, v79, v1
	v_add_f32_e32 v1, v82, v1
	v_pk_mul_f32 v[86:87], v[84:85], v[84:85]
	v_add_f32_e32 v1, v83, v1
	v_add_f32_e32 v1, v86, v1
	v_pk_mul_f32 v[90:91], v[88:89], v[88:89]
	v_add_f32_e32 v1, v87, v1
	v_add_f32_e32 v1, v90, v1
	v_pk_mul_f32 v[94:95], v[92:93], v[92:93]
	v_add_f32_e32 v1, v91, v1
	s_waitcnt vmcnt(13)
	v_lshlrev_b32_e32 v96, 16, v62
	v_and_b32_e32 v97, 0xffff0000, v62
	v_add_f32_e32 v1, v94, v1
	v_pk_mul_f32 v[98:99], v[96:97], v[96:97]
	v_add_f32_e32 v1, v95, v1
	v_lshlrev_b32_e32 v62, 16, v63
	v_and_b32_e32 v63, 0xffff0000, v63
	v_add_f32_e32 v1, v98, v1
	v_pk_mul_f32 v[100:101], v[62:63], v[62:63]
	v_add_f32_e32 v1, v99, v1
	v_add_f32_e32 v1, v100, v1
	v_add_f32_e32 v1, v101, v1
	s_waitcnt vmcnt(11)
	v_lshlrev_b32_e32 v82, 16, v64
	v_and_b32_e32 v83, 0xffff0000, v64
	v_add_f32_dpp v1, v1, v1 quad_perm:[1,0,3,2] row_mask:0xf bank_mask:0xf bound_ctrl:1
	v_pk_mul_f32 v[86:87], v[82:83], v[82:83]
	v_lshlrev_b32_e32 v64, 16, v65
	v_add_f32_dpp v1, v1, v1 quad_perm:[2,3,0,1] row_mask:0xf bank_mask:0xf bound_ctrl:1
	v_and_b32_e32 v65, 0xffff0000, v65
	v_pk_mul_f32 v[90:91], v[64:65], v[64:65]
	v_add_f32_dpp v1, v1, v1 row_half_mirror row_mask:0xf bank_mask:0xf bound_ctrl:1
	s_waitcnt vmcnt(9)
	v_lshlrev_b32_e32 v94, 16, v66
	v_and_b32_e32 v95, 0xffff0000, v66
	v_add_f32_dpp v1, v1, v1 row_mirror row_mask:0xf bank_mask:0xf bound_ctrl:1
	v_mov_b32_e32 v74, v1
	s_nop 1
	v_permlane16_swap_b32_e32 v1, v74
	v_add_f32_e32 v75, v1, v74
	v_add_f32_e32 v1, v86, v87
	v_add_f32_e32 v1, v90, v1
	v_pk_mul_f32 v[98:99], v[94:95], v[94:95]
	v_add_f32_e32 v1, v91, v1
	v_lshlrev_b32_e32 v66, 16, v67
	v_and_b32_e32 v67, 0xffff0000, v67
	v_add_f32_e32 v1, v98, v1
	v_pk_mul_f32 v[100:101], v[66:67], v[66:67]
	v_add_f32_e32 v1, v99, v1
	s_waitcnt vmcnt(7)
	v_lshlrev_b32_e32 v102, 16, v68
	v_and_b32_e32 v103, 0xffff0000, v68
	v_add_f32_e32 v1, v100, v1
	v_pk_mul_f32 v[104:105], v[102:103], v[102:103]
	v_add_f32_e32 v1, v101, v1
	v_lshlrev_b32_e32 v68, 16, v69
	v_and_b32_e32 v69, 0xffff0000, v69
	v_add_f32_e32 v1, v104, v1
	v_pk_mul_f32 v[106:107], v[68:69], v[68:69]
	v_add_f32_e32 v1, v105, v1
	s_waitcnt vmcnt(5)
; __device__ __forceinline__ void resid_norm(const float* hin, const u16* y, const float* gpost, const float* gpre, float* hout, u16* hn,
;                            int job0w, int jstridew) {
;     ...
;       ss = wave_sum(ss);
;       const float sc = rsqrtf(ss * (1.f / 1024.f) + 1e-6f);
;       float hv[16];
;       float s2 = 0.f;
; #pragma unroll
;       for (int i = 0; i < 4; i++) {
;         hv[i * 4 + 0] = h4[q][i].x + yv[i * 4 + 0] * sc * gp[i].x;
;         hv[i * 4 + 1] = h4[q][i].y + yv[i * 4 + 1] * sc * gp[i].y;
;         hv[i * 4 + 2] = h4[q][i].z + yv[i * 4 + 2] * sc * gp[i].z;
;         hv[i * 4 + 3] = h4[q][i].w + yv[i * 4 + 3] * sc * gp[i].w;
; #pragma unroll
;         for (int e = 0; e < 4; e++) s2 += hv[i * 4 + e] * hv[i * 4 + e];
;         __builtin_nontemporal_store((f32x4){hv[i * 4], hv[i * 4 + 1], hv[i * 4 + 2], hv[i * 4 + 3]}, (f32x4*)(hout + (size_t)r * 1024) + lane + i * 64);
;       }
	v_lshlrev_b32_e32 v108, 16, v70
	v_and_b32_e32 v109, 0xffff0000, v70
	v_add_f32_e32 v1, v106, v1
	v_pk_mul_f32 v[110:111], v[108:109], v[108:109]
	v_add_f32_e32 v1, v107, v1
	v_lshlrev_b32_e32 v70, 16, v71
	v_and_b32_e32 v71, 0xffff0000, v71
	v_add_f32_e32 v1, v110, v1
	v_pk_mul_f32 v[112:113], v[70:71], v[70:71]
	v_add_f32_e32 v1, v111, v1
	v_add_f32_e32 v1, v112, v1
	v_add_f32_e32 v1, v113, v1
	v_mov_b32_e32 v79, v75
	s_nop 1
	v_permlane32_swap_b32_e32 v75, v79
	v_add_f32_dpp v1, v1, v1 quad_perm:[1,0,3,2] row_mask:0xf bank_mask:0xf bound_ctrl:1
	s_nop 1
	v_add_f32_dpp v1, v1, v1 quad_perm:[2,3,0,1] row_mask:0xf bank_mask:0xf bound_ctrl:1
	s_nop 1
	v_add_f32_dpp v1, v1, v1 row_half_mirror row_mask:0xf bank_mask:0xf bound_ctrl:1
	s_nop 1
	v_add_f32_dpp v1, v1, v1 row_mirror row_mask:0xf bank_mask:0xf bound_ctrl:1
	v_mov_b32_e32 v74, v1
	s_nop 1
	v_permlane16_swap_b32_e32 v1, v74
	v_add_f32_e32 v74, v1, v74
	v_mov_b32_e32 v78, v74
	s_nop 1
	v_permlane32_swap_b32_e32 v74, v78
	v_pk_add_f32 v[74:75], v[74:75], v[78:79]
	s_nop 0
	v_pk_fma_f32 v[74:75], v[74:75], s[4:5], v[136:137] op_sel_hi:[1,0,0]
	s_nop 0
	v_mul_f32_e32 v1, 0x4b800000, v75
	v_cmp_gt_f32_e64 s[6:7], s85, v75
	v_cmp_gt_f32_e32 vcc, s85, v74
	s_nop 0
	v_cndmask_b32_e64 v1, v75, v1, s[6:7]
	v_rsq_f32_e32 v1, v1
	s_nop 0
	v_mul_f32_e32 v75, 0x45800000, v1
	v_cndmask_b32_e64 v78, v1, v75, s[6:7]
	v_pk_mul_f32 v[72:73], v[78:79], v[72:73] op_sel_hi:[0,1]
	v_pk_mul_f32 v[76:77], v[78:79], v[76:77] op_sel_hi:[0,1]
	s_waitcnt vmcnt(3)
	v_pk_fma_f32 v[16:17], v[48:49], v[76:77], v[16:17]
	v_pk_fma_f32 v[14:15], v[46:47], v[72:73], v[14:15]
	global_store_dwordx4 v[10:11], v[14:17], off offset:-4096 nt
	v_mul_f32_e32 v1, 0x4b800000, v74
	v_cndmask_b32_e32 v1, v74, v1, vcc
	v_pk_mul_f32 v[14:15], v[78:79], v[80:81] op_sel_hi:[0,1]
	v_pk_mul_f32 v[16:17], v[78:79], v[84:85] op_sel_hi:[0,1]
	s_waitcnt vmcnt(3)
	v_pk_fma_f32 v[16:17], v[52:53], v[16:17], v[20:21]
	v_pk_fma_f32 v[14:15], v[50:51], v[14:15], v[18:19]
	global_store_dwordx4 v[10:11], v[14:17], off offset:-3072 nt
	v_rsq_f32_e32 v1, v1
	s_nop 0
	v_pk_mul_f32 v[14:15], v[78:79], v[88:89] op_sel_hi:[0,1]
	v_pk_mul_f32 v[16:17], v[78:79], v[92:93] op_sel_hi:[0,1]
	s_waitcnt vmcnt(3)
	v_pk_fma_f32 v[16:17], v[56:57], v[16:17], v[24:25]
	v_pk_fma_f32 v[14:15], v[54:55], v[14:15], v[22:23]
	global_store_dwordx4 v[10:11], v[14:17], off offset:-2048 nt
	s_nop 1
	v_pk_mul_f32 v[14:15], v[78:79], v[96:97] op_sel_hi:[0,1]
	v_pk_mul_f32 v[16:17], v[78:79], v[62:63] op_sel_hi:[0,1]
	s_waitcnt vmcnt(3)
	v_pk_fma_f32 v[16:17], v[60:61], v[16:17], v[28:29]
	v_pk_fma_f32 v[14:15], v[58:59], v[14:15], v[26:27]
	global_store_dwordx4 v[10:11], v[14:17], off offset:-1024 nt
	s_nop 1
	v_mul_f32_e32 v14, 0x45800000, v1
	v_cndmask_b32_e32 v18, v1, v14, vcc
	v_pk_mul_f32 v[14:15], v[18:19], v[82:83] op_sel_hi:[0,1]
	v_pk_mul_f32 v[16:17], v[18:19], v[64:65] op_sel_hi:[0,1]
	v_pk_fma_f32 v[16:17], v[48:49], v[16:17], v[32:33]
	v_pk_fma_f32 v[14:15], v[46:47], v[14:15], v[30:31]
	global_store_dwordx4 v[10:11], v[14:17], off nt
	v_cmp_lt_i32_e32 vcc, s83, v0
	s_or_b64 s[10:11], vcc, s[10:11]
	v_pk_mul_f32 v[14:15], v[18:19], v[94:95] op_sel_hi:[0,1]
	v_pk_mul_f32 v[16:17], v[18:19], v[66:67] op_sel_hi:[0,1]
	v_pk_fma_f32 v[16:17], v[52:53], v[16:17], v[36:37]
	v_pk_fma_f32 v[14:15], v[50:51], v[14:15], v[34:35]
	global_store_dwordx4 v[10:11], v[14:17], off offset:1024 nt
	s_nop 1
	v_pk_mul_f32 v[14:15], v[18:19], v[102:103] op_sel_hi:[0,1]
	v_pk_mul_f32 v[16:17], v[18:19], v[68:69] op_sel_hi:[0,1]
	v_pk_fma_f32 v[16:17], v[56:57], v[16:17], v[40:41]
	v_pk_fma_f32 v[14:15], v[54:55], v[14:15], v[38:39]
	global_store_dwordx4 v[10:11], v[14:17], off offset:2048 nt
	s_nop 1
	v_pk_mul_f32 v[14:15], v[18:19], v[108:109] op_sel_hi:[0,1]
	v_pk_mul_f32 v[16:17], v[18:19], v[70:71] op_sel_hi:[0,1]
	v_pk_fma_f32 v[16:17], v[60:61], v[16:17], v[44:45]
	v_pk_fma_f32 v[14:15], v[58:59], v[14:15], v[42:43]
	global_store_dwordx4 v[10:11], v[14:17], off offset:3072 nt
	v_lshl_add_u64 v[10:11], v[10:11], 0, s[12:13]
	s_andn2_b64 exec, exec, s[10:11]
	s_cbranch_execnz .LBB0_88

; __device__ __forceinline__ void unpack4(uint2 u, float* f) { f[0] = bflo(u.x); f[1] = bfhi(u.x); f[2] = bflo(u.y); f[3] = bfhi(u.y); }
; __device__ __forceinline__ void resid_norm(const float* hin, const u16* y, const float* gpost, const float* gpre, float* hout, u16* hn,
;                            int job0w, int jstridew) {
;     ...
;   for (int r0 = job0w * RN_R; r0 < T_TOK; r0 += jstridew * RN_R) {
;     uint2 yu[RN_R][4];
;     float4 h4[RN_R][4];
; #pragma unroll
;     for (int q = 0; q < RN_R; q++)
; #pragma unroll
;       for (int i = 0; i < 4; i++) {
;         { typedef unsigned u32x2_ __attribute__((ext_vector_type(2)));
;           const u32x2_ t_ = __builtin_nontemporal_load((const u32x2_*)(y + (size_t)(r0 + q) * 1024 + (lane + i * 64) * 4));
;           yu[q][i] = make_uint2(t_[0], t_[1]); }
;         {
;           const f32x4 t_ = __builtin_nontemporal_load((const f32x4*)(hin + (size_t)(r0 + q) * 1024) + lane + i * 64);
;           h4[q][i] = make_float4(t_[0], t_[1], t_[2], t_[3]); }
;       }
;     float4 gp[4];
; #pragma unroll
;     for (int i = 0; i < 4; i++) gp[i] = ((const float4*)gpost)[lane + i * 64];
; #pragma unroll
;     for (int q = 0; q < RN_R; q++) {
;       const int r = r0 + q;
;       float yv[16];
;       float ss = 0.f;
; #pragma unroll
;       for (int i = 0; i < 4; i++) {
;         unpack4(yu[q][i], yv + i * 4);
; #pragma unroll
;         for (int e = 0; e < 4; e++) ss += yv[i * 4 + e] * yv[i * 4 + e];
;       }
;       ss = wave_sum(ss);
;       const float sc = rsqrtf(ss * (1.f / 1024.f) + 1e-6f);
;       float hv[16];
;       float s2 = 0.f;
; #pragma unroll
;       for (int i = 0; i < 4; i++) {
;         hv[i * 4 + 0] = h4[q][i].x + yv[i * 4 + 0] * sc * gp[i].x;
;         hv[i * 4 + 1] = h4[q][i].y + yv[i * 4 + 1] * sc * gp[i].y;
;         hv[i * 4 + 2] = h4[q][i].z + yv[i * 4 + 2] * sc * gp[i].z;
;         hv[i * 4 + 3] = h4[q][i].w + yv[i * 4 + 3] * sc * gp[i].w;
; #pragma unroll
;         for (int e = 0; e < 4; e++) s2 += hv[i * 4 + e] * hv[i * 4 + e];
.LBB0_206:
	v_lshl_add_u64 v[74:75], v[70:71], 0, v[134:135]
	global_load_dwordx4 v[32:35], v[66:67], off offset:-4096 nt
	global_load_dwordx4 v[36:39], v[66:67], off offset:-3072 nt
	global_load_dwordx4 v[40:43], v[66:67], off offset:-2048 nt
	global_load_dwordx4 v[44:47], v[66:67], off offset:-1024 nt
	global_load_dwordx4 v[4:7], v[66:67], off nt
	global_load_dwordx4 v[8:11], v[66:67], off offset:1024 nt
	global_load_dwordx4 v[12:15], v[66:67], off offset:2048 nt
	global_load_dwordx4 v[0:3], v[66:67], off offset:3072 nt
	global_load_dwordx4 v[16:19], v[50:51], off
	global_load_dwordx4 v[20:23], v[52:53], off
	global_load_dwordx4 v[24:27], v[54:55], off
	global_load_dwordx4 v[28:31], v[56:57], off
	global_load_dwordx2 v[76:77], v[74:75], off
	global_load_dwordx2 v[78:79], v[74:75], off offset:512
	global_load_dwordx2 v[80:81], v[74:75], off offset:1024
	global_load_dwordx2 v[82:83], v[74:75], off offset:1536
	global_load_dwordx2 v[84:85], v[74:75], off offset:2048
	global_load_dwordx2 v[86:87], v[74:75], off offset:2560
	global_load_dwordx2 v[88:89], v[74:75], off offset:3072
	s_nop 0
	global_load_dwordx2 v[74:75], v[74:75], off offset:3584
	v_lshl_add_u64 v[72:73], v[68:69], 0, v[134:135]
	v_add_u32_e32 v48, s14, v48
	v_lshl_add_u64 v[68:69], v[68:69], 0, s[12:13]
	v_lshl_add_u64 v[70:71], v[70:71], 0, s[12:13]
	s_waitcnt vmcnt(0)
	v_lshlrev_b32_e32 v90, 16, v76
	v_and_b32_e32 v91, 0xffff0000, v76
	v_lshlrev_b32_e32 v76, 16, v77
	v_and_b32_e32 v77, 0xffff0000, v77
	v_pk_mul_f32 v[108:109], v[76:77], v[76:77]
	v_lshlrev_b32_e32 v92, 16, v78
	v_and_b32_e32 v93, 0xffff0000, v78
	v_lshlrev_b32_e32 v104, 16, v74
	v_and_b32_e32 v105, 0xffff0000, v74
	v_lshlrev_b32_e32 v106, 16, v75
	v_and_b32_e32 v107, 0xffff0000, v75
	v_pk_mul_f32 v[74:75], v[90:91], v[90:91]
	v_pk_mul_f32 v[110:111], v[92:93], v[92:93]
	v_add_f32_e32 v49, v74, v75
	v_add_f32_e32 v49, v108, v49
	v_add_f32_e32 v49, v109, v49
	v_lshlrev_b32_e32 v78, 16, v79
	v_and_b32_e32 v79, 0xffff0000, v79
	v_add_f32_e32 v49, v110, v49
	v_lshlrev_b32_e32 v98, 16, v84
	v_and_b32_e32 v99, 0xffff0000, v84
	v_pk_mul_f32 v[112:113], v[78:79], v[78:79]
	v_add_f32_e32 v49, v111, v49
	v_lshlrev_b32_e32 v94, 16, v80
	v_and_b32_e32 v95, 0xffff0000, v80
	v_lshlrev_b32_e32 v84, 16, v85
	v_and_b32_e32 v85, 0xffff0000, v85
	v_pk_mul_f32 v[122:123], v[98:99], v[98:99]
	v_add_f32_e32 v49, v112, v49
	v_pk_mul_f32 v[114:115], v[94:95], v[94:95]
	v_pk_mul_f32 v[124:125], v[84:85], v[84:85]
	v_add_f32_e32 v74, v122, v123
	v_add_f32_e32 v49, v113, v49
	v_lshlrev_b32_e32 v80, 16, v81
	v_and_b32_e32 v81, 0xffff0000, v81
	v_lshlrev_b32_e32 v100, 16, v86
	v_and_b32_e32 v101, 0xffff0000, v86
	v_add_f32_e32 v74, v124, v74
	v_add_f32_e32 v49, v114, v49
	v_pk_mul_f32 v[116:117], v[80:81], v[80:81]
	v_pk_mul_f32 v[126:127], v[100:101], v[100:101]
	v_add_f32_e32 v74, v125, v74
	v_add_f32_e32 v49, v115, v49
	v_lshlrev_b32_e32 v96, 16, v82
	v_and_b32_e32 v97, 0xffff0000, v82
	v_lshlrev_b32_e32 v86, 16, v87
	v_and_b32_e32 v87, 0xffff0000, v87
	v_add_f32_e32 v74, v126, v74
	v_add_f32_e32 v49, v116, v49
	v_pk_mul_f32 v[118:119], v[96:97], v[96:97]
	v_pk_mul_f32 v[128:129], v[86:87], v[86:87]
	v_add_f32_e32 v74, v127, v74
	v_add_f32_e32 v49, v117, v49
	v_lshlrev_b32_e32 v82, 16, v83
	v_and_b32_e32 v83, 0xffff0000, v83
	v_lshlrev_b32_e32 v102, 16, v88
	v_and_b32_e32 v103, 0xffff0000, v88
	v_add_f32_e32 v74, v128, v74
	v_add_f32_e32 v49, v118, v49
	v_pk_mul_f32 v[120:121], v[82:83], v[82:83]
	v_pk_mul_f32 v[130:131], v[102:103], v[102:103]
	v_add_f32_e32 v74, v129, v74
	v_add_f32_e32 v49, v119, v49
	v_lshlrev_b32_e32 v88, 16, v89
	v_and_b32_e32 v89, 0xffff0000, v89
	v_add_f32_e32 v74, v130, v74
	v_add_f32_e32 v49, v120, v49
	v_pk_mul_f32 v[144:145], v[88:89], v[88:89]
	v_add_f32_e32 v74, v131, v74
	v_add_f32_e32 v49, v121, v49
	v_add_f32_e32 v74, v144, v74
	v_pk_mul_f32 v[146:147], v[104:105], v[104:105]
	v_add_f32_dpp v49, v49, v49 quad_perm:[1,0,3,2] row_mask:0xf bank_mask:0xf bound_ctrl:1
	v_add_f32_e32 v74, v145, v74
	v_add_f32_e32 v74, v146, v74
	v_add_f32_dpp v49, v49, v49 quad_perm:[2,3,0,1] row_mask:0xf bank_mask:0xf bound_ctrl:1
	v_pk_mul_f32 v[148:149], v[106:107], v[106:107]
	v_add_f32_e32 v74, v147, v74
	v_add_f32_dpp v49, v49, v49 row_half_mirror row_mask:0xf bank_mask:0xf bound_ctrl:1
	v_add_f32_e32 v108, v148, v74
	s_nop 0
	v_add_f32_dpp v49, v49, v49 row_mirror row_mask:0xf bank_mask:0xf bound_ctrl:1
	v_mov_b32_e32 v74, v49
	s_nop 1
	v_permlane16_swap_b32_e32 v49, v74
	v_add_f32_e32 v49, v49, v74
	v_mov_b32_e32 v74, v49
	s_nop 1
	v_permlane32_swap_b32_e32 v49, v74
	v_add_f32_e32 v49, v49, v74
	v_fmamk_f32 v49, v49, 0x3a800000, v136
	v_mul_f32_e32 v74, 0x4b800000, v49
	v_cmp_gt_f32_e32 vcc, s85, v49
	s_nop 1
	v_cndmask_b32_e32 v49, v49, v74, vcc
	v_rsq_f32_e32 v49, v49
	s_nop 0
	v_mul_f32_e32 v74, 0x45800000, v49
	v_cndmask_b32_e32 v74, v49, v74, vcc
	v_pk_mul_f32 v[90:91], v[74:75], v[90:91] op_sel_hi:[0,1]
	v_pk_mul_f32 v[76:77], v[74:75], v[76:77] op_sel_hi:[0,1]
	v_pk_mul_f32 v[92:93], v[74:75], v[92:93] op_sel_hi:[0,1]
	v_pk_mul_f32 v[78:79], v[74:75], v[78:79] op_sel_hi:[0,1]
	v_pk_mul_f32 v[94:95], v[74:75], v[94:95] op_sel_hi:[0,1]
	v_pk_mul_f32 v[80:81], v[74:75], v[80:81] op_sel_hi:[0,1]
	v_pk_mul_f32 v[96:97], v[74:75], v[96:97] op_sel_hi:[0,1]
	v_pk_mul_f32 v[74:75], v[74:75], v[82:83] op_sel_hi:[0,1]
	v_pk_fma_f32 v[32:33], v[16:17], v[90:91], v[32:33]
	v_pk_fma_f32 v[34:35], v[18:19], v[76:77], v[34:35]
	v_pk_fma_f32 v[36:37], v[20:21], v[92:93], v[36:37]
	v_pk_fma_f32 v[38:39], v[22:23], v[78:79], v[38:39]
	v_pk_fma_f32 v[40:41], v[24:25], v[94:95], v[40:41]
	v_pk_fma_f32 v[42:43], v[26:27], v[80:81], v[42:43]
; __device__ __forceinline__ uint2 pack4(float a, float b, float c, float d) { return make_uint2(pack2(a, b), pack2(c, d)); }
; __device__ __forceinline__ void resid_norm(const float* hin, const u16* y, const float* gpost, const float* gpre, float* hout, u16* hn,
;                            int job0w, int jstridew) {
;     ...
;         __builtin_nontemporal_store((f32x4){hv[i * 4], hv[i * 4 + 1], hv[i * 4 + 2], hv[i * 4 + 3]}, (f32x4*)(hout + (size_t)r * 1024) + lane + i * 64);
;       }
;       if (gpre) {
;         s2 = wave_sum(s2);
;         const float sc2 = rsqrtf(s2 * (1.f / 1024.f) + 1e-6f);
; #pragma unroll
;         for (int i = 0; i < 4; i++) {
;           float4 g = ((const float4*)gpre)[lane + i * 64];
;           *(uint2*)(hn + (size_t)r * 1024 + (lane + i * 64) * 4) =
;               pack4(hv[i * 4] * sc2 * g.x, hv[i * 4 + 1] * sc2 * g.y, hv[i * 4 + 2] * sc2 * g.z, hv[i * 4 + 3] * sc2 * g.w);
;         }
	v_pk_fma_f32 v[44:45], v[28:29], v[96:97], v[44:45]
	v_pk_fma_f32 v[46:47], v[30:31], v[74:75], v[46:47]
	global_store_dwordx4 v[66:67], v[32:35], off offset:-4096 nt
	global_store_dwordx4 v[66:67], v[36:39], off offset:-3072 nt
	global_store_dwordx4 v[66:67], v[40:43], off offset:-2048 nt
	global_store_dwordx4 v[66:67], v[44:47], off offset:-1024 nt
	global_load_dwordx4 v[74:77], v[58:59], off
	v_add_f32_e32 v49, v149, v108
	v_pk_mul_f32 v[82:83], v[32:33], v[32:33]
	v_pk_mul_f32 v[90:91], v[34:35], v[34:35]
	v_add_f32_dpp v49, v49, v49 quad_perm:[1,0,3,2] row_mask:0xf bank_mask:0xf bound_ctrl:1
	v_pk_mul_f32 v[92:93], v[36:37], v[36:37]
	v_pk_mul_f32 v[94:95], v[38:39], v[38:39]
	v_add_f32_dpp v49, v49, v49 quad_perm:[2,3,0,1] row_mask:0xf bank_mask:0xf bound_ctrl:1
	v_pk_mul_f32 v[96:97], v[40:41], v[40:41]
	v_pk_mul_f32 v[108:109], v[42:43], v[42:43]
	v_add_f32_dpp v49, v49, v49 row_half_mirror row_mask:0xf bank_mask:0xf bound_ctrl:1
	v_pk_mul_f32 v[110:111], v[44:45], v[44:45]
	v_pk_mul_f32 v[112:113], v[46:47], v[46:47]
	v_add_f32_dpp v49, v49, v49 row_mirror row_mask:0xf bank_mask:0xf bound_ctrl:1
	v_mov_b32_e32 v78, v49
	s_nop 1
	v_permlane16_swap_b32_e32 v49, v78
	v_add_f32_e32 v78, v49, v78
	v_add_f32_e32 v49, v82, v83
	v_add_f32_e32 v49, v90, v49
	v_add_f32_e32 v49, v91, v49
	v_add_f32_e32 v49, v92, v49
	v_add_f32_e32 v49, v93, v49
	v_add_f32_e32 v49, v94, v49
	v_add_f32_e32 v49, v95, v49
	v_add_f32_e32 v49, v96, v49
	v_add_f32_e32 v49, v97, v49
	v_add_f32_e32 v49, v108, v49
	v_add_f32_e32 v49, v109, v49
	v_add_f32_e32 v49, v110, v49
	v_add_f32_e32 v49, v111, v49
	v_add_f32_e32 v49, v112, v49
	v_add_f32_e32 v49, v113, v49
	v_mov_b32_e32 v80, v78
	s_nop 1
	v_permlane32_swap_b32_e32 v78, v80
	v_add_f32_dpp v49, v49, v49 quad_perm:[1,0,3,2] row_mask:0xf bank_mask:0xf bound_ctrl:1
	s_nop 1
	v_add_f32_dpp v49, v49, v49 quad_perm:[2,3,0,1] row_mask:0xf bank_mask:0xf bound_ctrl:1
	s_nop 1
	v_add_f32_dpp v49, v49, v49 row_half_mirror row_mask:0xf bank_mask:0xf bound_ctrl:1
	s_nop 1
	v_add_f32_dpp v49, v49, v49 row_mirror row_mask:0xf bank_mask:0xf bound_ctrl:1
	v_mov_b32_e32 v79, v49
	s_nop 1
	v_permlane16_swap_b32_e32 v49, v79
	v_add_f32_e32 v79, v49, v79
	v_mov_b32_e32 v81, v79
	s_nop 1
	v_permlane32_swap_b32_e32 v79, v81
	v_pk_add_f32 v[78:79], v[78:79], v[80:81]
	s_nop 0
	v_pk_fma_f32 v[78:79], v[78:79], s[4:5], v[136:137] op_sel_hi:[1,0,0]
	s_nop 0
	v_mul_f32_e32 v49, 0x4b800000, v79
	v_cmp_gt_f32_e32 vcc, s85, v79
	s_nop 1
	v_cndmask_b32_e32 v49, v79, v49, vcc
	v_rsq_f32_e32 v49, v49
	s_nop 0
	v_mul_f32_e32 v79, 0x45800000, v49
	v_cndmask_b32_e32 v80, v49, v79, vcc
	v_pk_mul_f32 v[32:33], v[32:33], v[80:81] op_sel_hi:[1,0]
	v_pk_mul_f32 v[34:35], v[34:35], v[80:81] op_sel_hi:[1,0]
	v_pk_mul_f32 v[36:37], v[36:37], v[80:81] op_sel_hi:[1,0]
	v_pk_mul_f32 v[38:39], v[38:39], v[80:81] op_sel_hi:[1,0]
	v_cmp_gt_f32_e32 vcc, s85, v78
	s_waitcnt vmcnt(0)
	v_pk_mul_f32 v[32:33], v[74:75], v[32:33]
	v_pk_mul_f32 v[34:35], v[76:77], v[34:35]
	v_cvt_pk_bf16_f32 v32, v32, v33
	v_cvt_pk_bf16_f32 v33, v34, v35
	global_store_dwordx2 v[72:73], v[32:33], off
	global_load_dwordx4 v[32:35], v[60:61], off
	s_waitcnt vmcnt(0)
	v_pk_mul_f32 v[32:33], v[32:33], v[36:37]
	v_pk_mul_f32 v[34:35], v[34:35], v[38:39]
	v_cvt_pk_bf16_f32 v32, v32, v33
	v_cvt_pk_bf16_f32 v33, v34, v35
	global_store_dwordx2 v[72:73], v[32:33], off offset:512
	global_load_dwordx4 v[32:35], v[62:63], off
	v_pk_mul_f32 v[36:37], v[40:41], v[80:81] op_sel_hi:[1,0]
	v_pk_mul_f32 v[38:39], v[42:43], v[80:81] op_sel_hi:[1,0]
	v_pk_mul_f32 v[40:41], v[46:47], v[80:81] op_sel_hi:[1,0]
	s_waitcnt vmcnt(0)
; __device__ __forceinline__ void unpack4(uint2 u, float* f) { f[0] = bflo(u.x); f[1] = bfhi(u.x); f[2] = bflo(u.y); f[3] = bfhi(u.y); }
; __device__ __forceinline__ uint2 pack4(float a, float b, float c, float d) { return make_uint2(pack2(a, b), pack2(c, d)); }
; __device__ __forceinline__ void resid_norm(const float* hin, const u16* y, const float* gpost, const float* gpre, float* hout, u16* hn,
;                            int job0w, int jstridew) {
;     ...
;     for (int q = 0; q < RN_R; q++) {
;       const int r = r0 + q;
;       float yv[16];
;       float ss = 0.f;
; #pragma unroll
;       for (int i = 0; i < 4; i++) {
;         unpack4(yu[q][i], yv + i * 4);
; #pragma unroll
;         for (int e = 0; e < 4; e++) ss += yv[i * 4 + e] * yv[i * 4 + e];
;       }
;       ss = wave_sum(ss);
;       const float sc = rsqrtf(ss * (1.f / 1024.f) + 1e-6f);
;       float hv[16];
;       float s2 = 0.f;
; #pragma unroll
;       for (int i = 0; i < 4; i++) {
;         hv[i * 4 + 0] = h4[q][i].x + yv[i * 4 + 0] * sc * gp[i].x;
;         hv[i * 4 + 1] = h4[q][i].y + yv[i * 4 + 1] * sc * gp[i].y;
;         hv[i * 4 + 2] = h4[q][i].z + yv[i * 4 + 2] * sc * gp[i].z;
;         hv[i * 4 + 3] = h4[q][i].w + yv[i * 4 + 3] * sc * gp[i].w;
; #pragma unroll
;         for (int e = 0; e < 4; e++) s2 += hv[i * 4 + e] * hv[i * 4 + e];
;         __builtin_nontemporal_store((f32x4){hv[i * 4], hv[i * 4 + 1], hv[i * 4 + 2], hv[i * 4 + 3]}, (f32x4*)(hout + (size_t)r * 1024) + lane + i * 64);
;       }
;       if (gpre) {
;         s2 = wave_sum(s2);
;         const float sc2 = rsqrtf(s2 * (1.f / 1024.f) + 1e-6f);
; #pragma unroll
;         for (int i = 0; i < 4; i++) {
;           float4 g = ((const float4*)gpre)[lane + i * 64];
;           *(uint2*)(hn + (size_t)r * 1024 + (lane + i * 64) * 4) =
;               pack4(hv[i * 4] * sc2 * g.x, hv[i * 4 + 1] * sc2 * g.y, hv[i * 4 + 2] * sc2 * g.z, hv[i * 4 + 3] * sc2 * g.w);
;         }
	v_pk_mul_f32 v[32:33], v[36:37], v[32:33]
	v_pk_mul_f32 v[34:35], v[38:39], v[34:35]
	v_cvt_pk_bf16_f32 v32, v32, v33
	v_cvt_pk_bf16_f32 v33, v34, v35
	global_store_dwordx2 v[72:73], v[32:33], off offset:1024
	global_load_dwordx4 v[32:35], v[64:65], off
	v_mul_f32_e32 v36, 0x4b800000, v78
	v_cndmask_b32_e32 v36, v78, v36, vcc
	v_rsq_f32_e32 v36, v36
	v_pk_mul_f32 v[38:39], v[44:45], v[80:81] op_sel_hi:[1,0]
	v_mul_f32_e32 v37, 0x45800000, v36
	v_cndmask_b32_e32 v36, v36, v37, vcc
	v_pk_mul_f32 v[42:43], v[36:37], v[98:99] op_sel_hi:[0,1]
	v_pk_mul_f32 v[44:45], v[36:37], v[84:85] op_sel_hi:[0,1]
	v_pk_fma_f32 v[4:5], v[16:17], v[42:43], v[4:5]
	v_pk_fma_f32 v[6:7], v[18:19], v[44:45], v[6:7]
	v_pk_mul_f32 v[46:47], v[36:37], v[100:101] op_sel_hi:[0,1]
	v_pk_mul_f32 v[74:75], v[36:37], v[86:87] op_sel_hi:[0,1]
	v_pk_mul_f32 v[76:77], v[36:37], v[102:103] op_sel_hi:[0,1]
	v_pk_mul_f32 v[78:79], v[36:37], v[88:89] op_sel_hi:[0,1]
	v_pk_mul_f32 v[80:81], v[36:37], v[104:105] op_sel_hi:[0,1]
	v_pk_mul_f32 v[36:37], v[36:37], v[106:107] op_sel_hi:[0,1]
	v_pk_fma_f32 v[8:9], v[20:21], v[46:47], v[8:9]
	v_pk_fma_f32 v[10:11], v[22:23], v[74:75], v[10:11]
	v_pk_fma_f32 v[12:13], v[24:25], v[76:77], v[12:13]
	v_pk_fma_f32 v[14:15], v[26:27], v[78:79], v[14:15]
	v_pk_fma_f32 v[0:1], v[28:29], v[80:81], v[0:1]
	v_pk_fma_f32 v[2:3], v[30:31], v[36:37], v[2:3]
	v_pk_mul_f32 v[20:21], v[4:5], v[4:5]
	v_pk_mul_f32 v[22:23], v[6:7], v[6:7]
	v_add_f32_e32 v20, v20, v21
	v_add_f32_e32 v20, v22, v20
	v_pk_mul_f32 v[24:25], v[8:9], v[8:9]
	v_add_f32_e32 v20, v23, v20
	v_add_f32_e32 v20, v24, v20
	v_pk_mul_f32 v[26:27], v[10:11], v[10:11]
	v_add_f32_e32 v20, v25, v20
	v_add_f32_e32 v20, v26, v20
	v_pk_mul_f32 v[28:29], v[12:13], v[12:13]
	v_add_f32_e32 v20, v27, v20
	v_add_f32_e32 v20, v28, v20
	v_pk_mul_f32 v[30:31], v[14:15], v[14:15]
	v_add_f32_e32 v20, v29, v20
	v_add_f32_e32 v20, v30, v20
	v_add_f32_e32 v20, v31, v20
	s_waitcnt vmcnt(0)
	v_pk_mul_f32 v[16:17], v[38:39], v[32:33]
	v_pk_mul_f32 v[18:19], v[40:41], v[34:35]
	v_cvt_pk_bf16_f32 v16, v16, v17
	v_cvt_pk_bf16_f32 v17, v18, v19
	global_store_dwordx2 v[72:73], v[16:17], off offset:1536
	global_store_dwordx4 v[66:67], v[4:7], off nt
	global_store_dwordx4 v[66:67], v[8:11], off offset:1024 nt
	global_store_dwordx4 v[66:67], v[12:15], off offset:2048 nt
	global_store_dwordx4 v[66:67], v[0:3], off offset:3072 nt
	global_load_dwordx4 v[16:19], v[58:59], off
	v_pk_mul_f32 v[32:33], v[0:1], v[0:1]
	v_pk_mul_f32 v[34:35], v[2:3], v[2:3]
	v_add_f32_e32 v20, v32, v20
	v_add_f32_e32 v20, v33, v20
	v_add_f32_e32 v20, v34, v20
	v_add_f32_e32 v20, v35, v20
	v_lshl_add_u64 v[66:67], v[66:67], 0, s[10:11]
	s_nop 0
	v_add_f32_dpp v20, v20, v20 quad_perm:[1,0,3,2] row_mask:0xf bank_mask:0xf bound_ctrl:1
	s_nop 1
	v_add_f32_dpp v20, v20, v20 quad_perm:[2,3,0,1] row_mask:0xf bank_mask:0xf bound_ctrl:1
	s_nop 1
	v_add_f32_dpp v20, v20, v20 row_half_mirror row_mask:0xf bank_mask:0xf bound_ctrl:1
	s_nop 1
	v_add_f32_dpp v20, v20, v20 row_mirror row_mask:0xf bank_mask:0xf bound_ctrl:1
	v_mov_b32_e32 v21, v20
	s_nop 1
	v_permlane16_swap_b32_e32 v20, v21
	v_add_f32_e32 v20, v20, v21
	v_mov_b32_e32 v21, v20
	s_nop 1
	v_permlane32_swap_b32_e32 v20, v21
	v_add_f32_e32 v20, v20, v21
	v_fmamk_f32 v20, v20, 0x3a800000, v136
	v_mul_f32_e32 v21, 0x4b800000, v20
	v_cmp_gt_f32_e32 vcc, s85, v20
	s_nop 1
	v_cndmask_b32_e32 v20, v20, v21, vcc
	v_rsq_f32_e32 v20, v20
	s_nop 0
	v_mul_f32_e32 v21, 0x45800000, v20
	v_cndmask_b32_e32 v20, v20, v21, vcc
	v_pk_mul_f32 v[4:5], v[4:5], v[20:21] op_sel_hi:[1,0]
	v_pk_mul_f32 v[6:7], v[6:7], v[20:21] op_sel_hi:[1,0]
	v_pk_mul_f32 v[8:9], v[8:9], v[20:21] op_sel_hi:[1,0]
	v_pk_mul_f32 v[10:11], v[10:11], v[20:21] op_sel_hi:[1,0]
	v_pk_mul_f32 v[0:1], v[0:1], v[20:21] op_sel_hi:[1,0]
	v_pk_mul_f32 v[2:3], v[2:3], v[20:21] op_sel_hi:[1,0]
	v_cmp_lt_i32_e32 vcc, s83, v48
	s_or_b64 s[8:9], vcc, s[8:9]
	s_waitcnt vmcnt(0)
	v_pk_mul_f32 v[4:5], v[16:17], v[4:5]
	v_pk_mul_f32 v[6:7], v[18:19], v[6:7]
	v_cvt_pk_bf16_f32 v4, v4, v5
	v_cvt_pk_bf16_f32 v5, v6, v7
	global_store_dwordx2 v[72:73], v[4:5], off offset:2048
	global_load_dwordx4 v[4:7], v[60:61], off
	s_waitcnt vmcnt(0)
	v_pk_mul_f32 v[4:5], v[4:5], v[8:9]
	v_pk_mul_f32 v[6:7], v[6:7], v[10:11]
	v_cvt_pk_bf16_f32 v4, v4, v5
	v_cvt_pk_bf16_f32 v5, v6, v7
	global_store_dwordx2 v[72:73], v[4:5], off offset:2560
	global_load_dwordx4 v[4:7], v[62:63], off
	v_pk_mul_f32 v[8:9], v[12:13], v[20:21] op_sel_hi:[1,0]
	v_pk_mul_f32 v[10:11], v[14:15], v[20:21] op_sel_hi:[1,0]
	s_waitcnt vmcnt(0)
	v_pk_mul_f32 v[4:5], v[8:9], v[4:5]
	v_pk_mul_f32 v[6:7], v[10:11], v[6:7]
	v_cvt_pk_bf16_f32 v4, v4, v5
	v_cvt_pk_bf16_f32 v5, v6, v7
	global_store_dwordx2 v[72:73], v[4:5], off offset:3072
	global_load_dwordx4 v[4:7], v[64:65], off
	s_waitcnt vmcnt(0)
	v_pk_mul_f32 v[0:1], v[0:1], v[4:5]
	v_pk_mul_f32 v[2:3], v[2:3], v[6:7]
	v_cvt_pk_bf16_f32 v0, v0, v1
	v_cvt_pk_bf16_f32 v1, v2, v3
	global_store_dwordx2 v[72:73], v[0:1], off offset:3584
	s_andn2_b64 exec, exec, s[8:9]
	s_cbranch_execnz .LBB0_206

; __device__ __forceinline__ void unpack4(uint2 u, float* f) { f[0] = bflo(u.x); f[1] = bfhi(u.x); f[2] = bflo(u.y); f[3] = bfhi(u.y); }
; __device__ __forceinline__ void resid_norm(const float* hin, const u16* y, const float* gpost, const float* gpre, float* hout, u16* hn,
;                            int job0w, int jstridew) {
;     ...
;   for (int r0 = job0w * RN_R; r0 < T_TOK; r0 += jstridew * RN_R) {
;     uint2 yu[RN_R][4];
;     float4 h4[RN_R][4];
; #pragma unroll
;     for (int q = 0; q < RN_R; q++)
; #pragma unroll
;       for (int i = 0; i < 4; i++) {
;         { typedef unsigned u32x2_ __attribute__((ext_vector_type(2)));
;           const u32x2_ t_ = __builtin_nontemporal_load((const u32x2_*)(y + (size_t)(r0 + q) * 1024 + (lane + i * 64) * 4));
;           yu[q][i] = make_uint2(t_[0], t_[1]); }
;         {
;           const f32x4 t_ = __builtin_nontemporal_load((const f32x4*)(hin + (size_t)(r0 + q) * 1024) + lane + i * 64);
;           h4[q][i] = make_float4(t_[0], t_[1], t_[2], t_[3]); }
;       }
;     float4 gp[4];
; #pragma unroll
;     for (int i = 0; i < 4; i++) gp[i] = ((const float4*)gpost)[lane + i * 64];
; #pragma unroll
;     for (int q = 0; q < RN_R; q++) {
;       const int r = r0 + q;
;       float yv[16];
;       float ss = 0.f;
; #pragma unroll
;       for (int i = 0; i < 4; i++) {
;         unpack4(yu[q][i], yv + i * 4);
; #pragma unroll
;         for (int e = 0; e < 4; e++) ss += yv[i * 4 + e] * yv[i * 4 + e];
;       }
;       ss = wave_sum(ss);
;       const float sc = rsqrtf(ss * (1.f / 1024.f) + 1e-6f);
;       float hv[16];
;       float s2 = 0.f;
; #pragma unroll
;       for (int i = 0; i < 4; i++) {
;         hv[i * 4 + 0] = h4[q][i].x + yv[i * 4 + 0] * sc * gp[i].x;
;         hv[i * 4 + 1] = h4[q][i].y + yv[i * 4 + 1] * sc * gp[i].y;
;         hv[i * 4 + 2] = h4[q][i].z + yv[i * 4 + 2] * sc * gp[i].z;
;         hv[i * 4 + 3] = h4[q][i].w + yv[i * 4 + 3] * sc * gp[i].w;
; #pragma unroll
;         for (int e = 0; e < 4; e++) s2 += hv[i * 4 + e] * hv[i * 4 + e];
.LBB0_231:
	v_lshl_add_u64 v[74:75], v[70:71], 0, v[134:135]
	global_load_dwordx4 v[32:35], v[66:67], off offset:-4096 nt
	global_load_dwordx4 v[36:39], v[66:67], off offset:-3072 nt
	global_load_dwordx4 v[40:43], v[66:67], off offset:-2048 nt
	global_load_dwordx4 v[44:47], v[66:67], off offset:-1024 nt
	global_load_dwordx4 v[4:7], v[66:67], off nt
	global_load_dwordx4 v[8:11], v[66:67], off offset:1024 nt
	global_load_dwordx4 v[12:15], v[66:67], off offset:2048 nt
	global_load_dwordx4 v[0:3], v[66:67], off offset:3072 nt
	global_load_dwordx4 v[16:19], v[50:51], off
	global_load_dwordx4 v[20:23], v[52:53], off
	global_load_dwordx4 v[24:27], v[54:55], off
	global_load_dwordx4 v[28:31], v[56:57], off
	global_load_dwordx2 v[76:77], v[74:75], off
	global_load_dwordx2 v[78:79], v[74:75], off offset:512
	global_load_dwordx2 v[80:81], v[74:75], off offset:1024
	global_load_dwordx2 v[82:83], v[74:75], off offset:1536
	global_load_dwordx2 v[84:85], v[74:75], off offset:2048
	global_load_dwordx2 v[86:87], v[74:75], off offset:2560
	global_load_dwordx2 v[88:89], v[74:75], off offset:3072
	s_nop 0
	global_load_dwordx2 v[74:75], v[74:75], off offset:3584
	v_lshl_add_u64 v[72:73], v[68:69], 0, v[134:135]
	v_add_u32_e32 v48, s34, v48
	v_lshl_add_u64 v[68:69], v[68:69], 0, s[16:17]
	v_lshl_add_u64 v[70:71], v[70:71], 0, s[16:17]
	s_waitcnt vmcnt(0)
	v_lshlrev_b32_e32 v90, 16, v76
	v_and_b32_e32 v91, 0xffff0000, v76
	v_lshlrev_b32_e32 v76, 16, v77
	v_and_b32_e32 v77, 0xffff0000, v77
	v_pk_mul_f32 v[108:109], v[76:77], v[76:77]
	v_lshlrev_b32_e32 v92, 16, v78
	v_and_b32_e32 v93, 0xffff0000, v78
	v_lshlrev_b32_e32 v104, 16, v74
	v_and_b32_e32 v105, 0xffff0000, v74
	v_lshlrev_b32_e32 v106, 16, v75
	v_and_b32_e32 v107, 0xffff0000, v75
	v_pk_mul_f32 v[74:75], v[90:91], v[90:91]
	v_pk_mul_f32 v[110:111], v[92:93], v[92:93]
	v_add_f32_e32 v49, v74, v75
	v_add_f32_e32 v49, v108, v49
	v_add_f32_e32 v49, v109, v49
	v_lshlrev_b32_e32 v78, 16, v79
	v_and_b32_e32 v79, 0xffff0000, v79
	v_add_f32_e32 v49, v110, v49
	v_lshlrev_b32_e32 v98, 16, v84
	v_and_b32_e32 v99, 0xffff0000, v84
	v_pk_mul_f32 v[112:113], v[78:79], v[78:79]
	v_add_f32_e32 v49, v111, v49
	v_lshlrev_b32_e32 v94, 16, v80
	v_and_b32_e32 v95, 0xffff0000, v80
	v_lshlrev_b32_e32 v84, 16, v85
	v_and_b32_e32 v85, 0xffff0000, v85
	v_pk_mul_f32 v[122:123], v[98:99], v[98:99]
	v_add_f32_e32 v49, v112, v49
	v_pk_mul_f32 v[114:115], v[94:95], v[94:95]
	v_pk_mul_f32 v[124:125], v[84:85], v[84:85]
	v_add_f32_e32 v74, v122, v123
	v_add_f32_e32 v49, v113, v49
	v_lshlrev_b32_e32 v80, 16, v81
	v_and_b32_e32 v81, 0xffff0000, v81
	v_lshlrev_b32_e32 v100, 16, v86
	v_and_b32_e32 v101, 0xffff0000, v86
	v_add_f32_e32 v74, v124, v74
	v_add_f32_e32 v49, v114, v49
	v_pk_mul_f32 v[116:117], v[80:81], v[80:81]
	v_pk_mul_f32 v[126:127], v[100:101], v[100:101]
	v_add_f32_e32 v74, v125, v74
	v_add_f32_e32 v49, v115, v49
	v_lshlrev_b32_e32 v96, 16, v82
	v_and_b32_e32 v97, 0xffff0000, v82
	v_lshlrev_b32_e32 v86, 16, v87
	v_and_b32_e32 v87, 0xffff0000, v87
	v_add_f32_e32 v74, v126, v74
	v_add_f32_e32 v49, v116, v49
	v_pk_mul_f32 v[118:119], v[96:97], v[96:97]
	v_pk_mul_f32 v[128:129], v[86:87], v[86:87]
	v_add_f32_e32 v74, v127, v74
	v_add_f32_e32 v49, v117, v49
	v_lshlrev_b32_e32 v82, 16, v83
	v_and_b32_e32 v83, 0xffff0000, v83
	v_lshlrev_b32_e32 v102, 16, v88
	v_and_b32_e32 v103, 0xffff0000, v88
	v_add_f32_e32 v74, v128, v74
	v_add_f32_e32 v49, v118, v49
	v_pk_mul_f32 v[120:121], v[82:83], v[82:83]
	v_pk_mul_f32 v[130:131], v[102:103], v[102:103]
	v_add_f32_e32 v74, v129, v74
	v_add_f32_e32 v49, v119, v49
	v_lshlrev_b32_e32 v88, 16, v89
	v_and_b32_e32 v89, 0xffff0000, v89
	v_add_f32_e32 v74, v130, v74
	v_add_f32_e32 v49, v120, v49
	v_pk_mul_f32 v[144:145], v[88:89], v[88:89]
	v_add_f32_e32 v74, v131, v74
	v_add_f32_e32 v49, v121, v49
	v_add_f32_e32 v74, v144, v74
	v_pk_mul_f32 v[146:147], v[104:105], v[104:105]
	v_add_f32_dpp v49, v49, v49 quad_perm:[1,0,3,2] row_mask:0xf bank_mask:0xf bound_ctrl:1
	v_add_f32_e32 v74, v145, v74
	v_add_f32_e32 v74, v146, v74
	v_add_f32_dpp v49, v49, v49 quad_perm:[2,3,0,1] row_mask:0xf bank_mask:0xf bound_ctrl:1
	v_pk_mul_f32 v[148:149], v[106:107], v[106:107]
	v_add_f32_e32 v74, v147, v74
	v_add_f32_dpp v49, v49, v49 row_half_mirror row_mask:0xf bank_mask:0xf bound_ctrl:1
	v_add_f32_e32 v108, v148, v74
	s_nop 0
	v_add_f32_dpp v49, v49, v49 row_mirror row_mask:0xf bank_mask:0xf bound_ctrl:1
	v_mov_b32_e32 v74, v49
	s_nop 1
	v_permlane16_swap_b32_e32 v49, v74
	v_add_f32_e32 v49, v49, v74
	v_mov_b32_e32 v74, v49
	s_nop 1
	v_permlane32_swap_b32_e32 v49, v74
	v_add_f32_e32 v49, v49, v74
	v_fmamk_f32 v49, v49, 0x3a800000, v136
	v_mul_f32_e32 v74, 0x4b800000, v49
	v_cmp_gt_f32_e32 vcc, s85, v49
	s_nop 1
	v_cndmask_b32_e32 v49, v49, v74, vcc
	v_rsq_f32_e32 v49, v49
	s_nop 0
	v_mul_f32_e32 v74, 0x45800000, v49
	v_cndmask_b32_e32 v74, v49, v74, vcc
	v_pk_mul_f32 v[90:91], v[74:75], v[90:91] op_sel_hi:[0,1]
	v_pk_mul_f32 v[76:77], v[74:75], v[76:77] op_sel_hi:[0,1]
	v_pk_mul_f32 v[92:93], v[74:75], v[92:93] op_sel_hi:[0,1]
	v_pk_mul_f32 v[78:79], v[74:75], v[78:79] op_sel_hi:[0,1]
	v_pk_mul_f32 v[94:95], v[74:75], v[94:95] op_sel_hi:[0,1]
	v_pk_mul_f32 v[80:81], v[74:75], v[80:81] op_sel_hi:[0,1]
	v_pk_mul_f32 v[96:97], v[74:75], v[96:97] op_sel_hi:[0,1]
	v_pk_mul_f32 v[74:75], v[74:75], v[82:83] op_sel_hi:[0,1]
	v_pk_fma_f32 v[32:33], v[16:17], v[90:91], v[32:33]
	v_pk_fma_f32 v[34:35], v[18:19], v[76:77], v[34:35]
	v_pk_fma_f32 v[36:37], v[20:21], v[92:93], v[36:37]
	v_pk_fma_f32 v[38:39], v[22:23], v[78:79], v[38:39]
	v_pk_fma_f32 v[40:41], v[24:25], v[94:95], v[40:41]
	v_pk_fma_f32 v[42:43], v[26:27], v[80:81], v[42:43]
; __device__ __forceinline__ uint2 pack4(float a, float b, float c, float d) { return make_uint2(pack2(a, b), pack2(c, d)); }
; __device__ __forceinline__ void resid_norm(const float* hin, const u16* y, const float* gpost, const float* gpre, float* hout, u16* hn,
;                            int job0w, int jstridew) {
;     ...
;         __builtin_nontemporal_store((f32x4){hv[i * 4], hv[i * 4 + 1], hv[i * 4 + 2], hv[i * 4 + 3]}, (f32x4*)(hout + (size_t)r * 1024) + lane + i * 64);
;       }
;       if (gpre) {
;         s2 = wave_sum(s2);
;         const float sc2 = rsqrtf(s2 * (1.f / 1024.f) + 1e-6f);
; #pragma unroll
;         for (int i = 0; i < 4; i++) {
;           float4 g = ((const float4*)gpre)[lane + i * 64];
;           *(uint2*)(hn + (size_t)r * 1024 + (lane + i * 64) * 4) =
;               pack4(hv[i * 4] * sc2 * g.x, hv[i * 4 + 1] * sc2 * g.y, hv[i * 4 + 2] * sc2 * g.z, hv[i * 4 + 3] * sc2 * g.w);
;         }
	v_pk_fma_f32 v[44:45], v[28:29], v[96:97], v[44:45]
	v_pk_fma_f32 v[46:47], v[30:31], v[74:75], v[46:47]
	global_store_dwordx4 v[66:67], v[32:35], off offset:-4096 nt
	global_store_dwordx4 v[66:67], v[36:39], off offset:-3072 nt
	global_store_dwordx4 v[66:67], v[40:43], off offset:-2048 nt
	global_store_dwordx4 v[66:67], v[44:47], off offset:-1024 nt
	global_load_dwordx4 v[74:77], v[58:59], off
	v_add_f32_e32 v49, v149, v108
	v_pk_mul_f32 v[82:83], v[32:33], v[32:33]
	v_pk_mul_f32 v[90:91], v[34:35], v[34:35]
	v_add_f32_dpp v49, v49, v49 quad_perm:[1,0,3,2] row_mask:0xf bank_mask:0xf bound_ctrl:1
	v_pk_mul_f32 v[92:93], v[36:37], v[36:37]
	v_pk_mul_f32 v[94:95], v[38:39], v[38:39]
	v_add_f32_dpp v49, v49, v49 quad_perm:[2,3,0,1] row_mask:0xf bank_mask:0xf bound_ctrl:1
	v_pk_mul_f32 v[96:97], v[40:41], v[40:41]
	v_pk_mul_f32 v[108:109], v[42:43], v[42:43]
	v_add_f32_dpp v49, v49, v49 row_half_mirror row_mask:0xf bank_mask:0xf bound_ctrl:1
	v_pk_mul_f32 v[110:111], v[44:45], v[44:45]
	v_pk_mul_f32 v[112:113], v[46:47], v[46:47]
	v_add_f32_dpp v49, v49, v49 row_mirror row_mask:0xf bank_mask:0xf bound_ctrl:1
	v_mov_b32_e32 v78, v49
	s_nop 1
	v_permlane16_swap_b32_e32 v49, v78
	v_add_f32_e32 v78, v49, v78
	v_add_f32_e32 v49, v82, v83
	v_add_f32_e32 v49, v90, v49
	v_add_f32_e32 v49, v91, v49
	v_add_f32_e32 v49, v92, v49
	v_add_f32_e32 v49, v93, v49
	v_add_f32_e32 v49, v94, v49
	v_add_f32_e32 v49, v95, v49
	v_add_f32_e32 v49, v96, v49
	v_add_f32_e32 v49, v97, v49
	v_add_f32_e32 v49, v108, v49
	v_add_f32_e32 v49, v109, v49
	v_add_f32_e32 v49, v110, v49
	v_add_f32_e32 v49, v111, v49
	v_add_f32_e32 v49, v112, v49
	v_add_f32_e32 v49, v113, v49
	v_mov_b32_e32 v80, v78
	s_nop 1
	v_permlane32_swap_b32_e32 v78, v80
	v_add_f32_dpp v49, v49, v49 quad_perm:[1,0,3,2] row_mask:0xf bank_mask:0xf bound_ctrl:1
	s_nop 1
	v_add_f32_dpp v49, v49, v49 quad_perm:[2,3,0,1] row_mask:0xf bank_mask:0xf bound_ctrl:1
	s_nop 1
	v_add_f32_dpp v49, v49, v49 row_half_mirror row_mask:0xf bank_mask:0xf bound_ctrl:1
	s_nop 1
	v_add_f32_dpp v49, v49, v49 row_mirror row_mask:0xf bank_mask:0xf bound_ctrl:1
	v_mov_b32_e32 v79, v49
	s_nop 1
	v_permlane16_swap_b32_e32 v49, v79
	v_add_f32_e32 v79, v49, v79
	v_mov_b32_e32 v81, v79
	s_nop 1
	v_permlane32_swap_b32_e32 v79, v81
	v_pk_add_f32 v[78:79], v[78:79], v[80:81]
	s_nop 0
	v_pk_fma_f32 v[78:79], v[78:79], s[4:5], v[136:137] op_sel_hi:[1,0,0]
	s_nop 0
	v_mul_f32_e32 v49, 0x4b800000, v79
	v_cmp_gt_f32_e32 vcc, s85, v79
	s_nop 1
	v_cndmask_b32_e32 v49, v79, v49, vcc
	v_rsq_f32_e32 v49, v49
	s_nop 0
	v_mul_f32_e32 v79, 0x45800000, v49
	v_cndmask_b32_e32 v80, v49, v79, vcc
	v_pk_mul_f32 v[32:33], v[32:33], v[80:81] op_sel_hi:[1,0]
	v_pk_mul_f32 v[34:35], v[34:35], v[80:81] op_sel_hi:[1,0]
	v_pk_mul_f32 v[36:37], v[36:37], v[80:81] op_sel_hi:[1,0]
	v_pk_mul_f32 v[38:39], v[38:39], v[80:81] op_sel_hi:[1,0]
	v_cmp_gt_f32_e32 vcc, s85, v78
	s_waitcnt vmcnt(0)
	v_pk_mul_f32 v[32:33], v[74:75], v[32:33]
	v_pk_mul_f32 v[34:35], v[76:77], v[34:35]
	v_cvt_pk_bf16_f32 v32, v32, v33
	v_cvt_pk_bf16_f32 v33, v34, v35
	global_store_dwordx2 v[72:73], v[32:33], off
	global_load_dwordx4 v[32:35], v[60:61], off
	s_waitcnt vmcnt(0)
	v_pk_mul_f32 v[32:33], v[32:33], v[36:37]
	v_pk_mul_f32 v[34:35], v[34:35], v[38:39]
	v_cvt_pk_bf16_f32 v32, v32, v33
	v_cvt_pk_bf16_f32 v33, v34, v35
	global_store_dwordx2 v[72:73], v[32:33], off offset:512
	global_load_dwordx4 v[32:35], v[62:63], off
	v_pk_mul_f32 v[36:37], v[40:41], v[80:81] op_sel_hi:[1,0]
	v_pk_mul_f32 v[38:39], v[42:43], v[80:81] op_sel_hi:[1,0]
	v_pk_mul_f32 v[40:41], v[46:47], v[80:81] op_sel_hi:[1,0]
	s_waitcnt vmcnt(0)
; __device__ __forceinline__ void unpack4(uint2 u, float* f) { f[0] = bflo(u.x); f[1] = bfhi(u.x); f[2] = bflo(u.y); f[3] = bfhi(u.y); }
; __device__ __forceinline__ uint2 pack4(float a, float b, float c, float d) { return make_uint2(pack2(a, b), pack2(c, d)); }
; __device__ __forceinline__ void resid_norm(const float* hin, const u16* y, const float* gpost, const float* gpre, float* hout, u16* hn,
;                            int job0w, int jstridew) {
;     ...
;     for (int q = 0; q < RN_R; q++) {
;       const int r = r0 + q;
;       float yv[16];
;       float ss = 0.f;
; #pragma unroll
;       for (int i = 0; i < 4; i++) {
;         unpack4(yu[q][i], yv + i * 4);
; #pragma unroll
;         for (int e = 0; e < 4; e++) ss += yv[i * 4 + e] * yv[i * 4 + e];
;       }
;       ss = wave_sum(ss);
;       const float sc = rsqrtf(ss * (1.f / 1024.f) + 1e-6f);
;       float hv[16];
;       float s2 = 0.f;
; #pragma unroll
;       for (int i = 0; i < 4; i++) {
;         hv[i * 4 + 0] = h4[q][i].x + yv[i * 4 + 0] * sc * gp[i].x;
;         hv[i * 4 + 1] = h4[q][i].y + yv[i * 4 + 1] * sc * gp[i].y;
;         hv[i * 4 + 2] = h4[q][i].z + yv[i * 4 + 2] * sc * gp[i].z;
;         hv[i * 4 + 3] = h4[q][i].w + yv[i * 4 + 3] * sc * gp[i].w;
; #pragma unroll
;         for (int e = 0; e < 4; e++) s2 += hv[i * 4 + e] * hv[i * 4 + e];
;         __builtin_nontemporal_store((f32x4){hv[i * 4], hv[i * 4 + 1], hv[i * 4 + 2], hv[i * 4 + 3]}, (f32x4*)(hout + (size_t)r * 1024) + lane + i * 64);
;       }
;       if (gpre) {
;         s2 = wave_sum(s2);
;         const float sc2 = rsqrtf(s2 * (1.f / 1024.f) + 1e-6f);
; #pragma unroll
;         for (int i = 0; i < 4; i++) {
;           float4 g = ((const float4*)gpre)[lane + i * 64];
;           *(uint2*)(hn + (size_t)r * 1024 + (lane + i * 64) * 4) =
;               pack4(hv[i * 4] * sc2 * g.x, hv[i * 4 + 1] * sc2 * g.y, hv[i * 4 + 2] * sc2 * g.z, hv[i * 4 + 3] * sc2 * g.w);
;         }
	v_pk_mul_f32 v[32:33], v[36:37], v[32:33]
	v_pk_mul_f32 v[34:35], v[38:39], v[34:35]
	v_cvt_pk_bf16_f32 v32, v32, v33
	v_cvt_pk_bf16_f32 v33, v34, v35
	global_store_dwordx2 v[72:73], v[32:33], off offset:1024
	global_load_dwordx4 v[32:35], v[64:65], off
	v_mul_f32_e32 v36, 0x4b800000, v78
	v_cndmask_b32_e32 v36, v78, v36, vcc
	v_rsq_f32_e32 v36, v36
	v_pk_mul_f32 v[38:39], v[44:45], v[80:81] op_sel_hi:[1,0]
	v_mul_f32_e32 v37, 0x45800000, v36
	v_cndmask_b32_e32 v36, v36, v37, vcc
	v_pk_mul_f32 v[42:43], v[36:37], v[98:99] op_sel_hi:[0,1]
	v_pk_mul_f32 v[44:45], v[36:37], v[84:85] op_sel_hi:[0,1]
	v_pk_fma_f32 v[4:5], v[16:17], v[42:43], v[4:5]
	v_pk_fma_f32 v[6:7], v[18:19], v[44:45], v[6:7]
	v_pk_mul_f32 v[46:47], v[36:37], v[100:101] op_sel_hi:[0,1]
	v_pk_mul_f32 v[74:75], v[36:37], v[86:87] op_sel_hi:[0,1]
	v_pk_mul_f32 v[76:77], v[36:37], v[102:103] op_sel_hi:[0,1]
	v_pk_mul_f32 v[78:79], v[36:37], v[88:89] op_sel_hi:[0,1]
	v_pk_mul_f32 v[80:81], v[36:37], v[104:105] op_sel_hi:[0,1]
	v_pk_mul_f32 v[36:37], v[36:37], v[106:107] op_sel_hi:[0,1]
	v_pk_fma_f32 v[8:9], v[20:21], v[46:47], v[8:9]
	v_pk_fma_f32 v[10:11], v[22:23], v[74:75], v[10:11]
	v_pk_fma_f32 v[12:13], v[24:25], v[76:77], v[12:13]
	v_pk_fma_f32 v[14:15], v[26:27], v[78:79], v[14:15]
	v_pk_fma_f32 v[0:1], v[28:29], v[80:81], v[0:1]
	v_pk_fma_f32 v[2:3], v[30:31], v[36:37], v[2:3]
	v_pk_mul_f32 v[20:21], v[4:5], v[4:5]
	v_pk_mul_f32 v[22:23], v[6:7], v[6:7]
	v_add_f32_e32 v20, v20, v21
	v_add_f32_e32 v20, v22, v20
	v_pk_mul_f32 v[24:25], v[8:9], v[8:9]
	v_add_f32_e32 v20, v23, v20
	v_add_f32_e32 v20, v24, v20
	v_pk_mul_f32 v[26:27], v[10:11], v[10:11]
	v_add_f32_e32 v20, v25, v20
	v_add_f32_e32 v20, v26, v20
	v_pk_mul_f32 v[28:29], v[12:13], v[12:13]
	v_add_f32_e32 v20, v27, v20
	v_add_f32_e32 v20, v28, v20
	v_pk_mul_f32 v[30:31], v[14:15], v[14:15]
	v_add_f32_e32 v20, v29, v20
	v_add_f32_e32 v20, v30, v20
	v_add_f32_e32 v20, v31, v20
	s_waitcnt vmcnt(0)
	v_pk_mul_f32 v[16:17], v[38:39], v[32:33]
	v_pk_mul_f32 v[18:19], v[40:41], v[34:35]
	v_cvt_pk_bf16_f32 v16, v16, v17
	v_cvt_pk_bf16_f32 v17, v18, v19
	global_store_dwordx2 v[72:73], v[16:17], off offset:1536
	global_store_dwordx4 v[66:67], v[4:7], off nt
	global_store_dwordx4 v[66:67], v[8:11], off offset:1024 nt
	global_store_dwordx4 v[66:67], v[12:15], off offset:2048 nt
	global_store_dwordx4 v[66:67], v[0:3], off offset:3072 nt
	global_load_dwordx4 v[16:19], v[58:59], off
	v_pk_mul_f32 v[32:33], v[0:1], v[0:1]
	v_pk_mul_f32 v[34:35], v[2:3], v[2:3]
	v_add_f32_e32 v20, v32, v20
	v_add_f32_e32 v20, v33, v20
	v_add_f32_e32 v20, v34, v20
	v_add_f32_e32 v20, v35, v20
	v_lshl_add_u64 v[66:67], v[66:67], 0, s[14:15]
	s_nop 0
	v_add_f32_dpp v20, v20, v20 quad_perm:[1,0,3,2] row_mask:0xf bank_mask:0xf bound_ctrl:1
	s_nop 1
	v_add_f32_dpp v20, v20, v20 quad_perm:[2,3,0,1] row_mask:0xf bank_mask:0xf bound_ctrl:1
	s_nop 1
	v_add_f32_dpp v20, v20, v20 row_half_mirror row_mask:0xf bank_mask:0xf bound_ctrl:1
	s_nop 1
	v_add_f32_dpp v20, v20, v20 row_mirror row_mask:0xf bank_mask:0xf bound_ctrl:1
	v_mov_b32_e32 v21, v20
	s_nop 1
	v_permlane16_swap_b32_e32 v20, v21
	v_add_f32_e32 v20, v20, v21
	v_mov_b32_e32 v21, v20
	s_nop 1
	v_permlane32_swap_b32_e32 v20, v21
	v_add_f32_e32 v20, v20, v21
	v_fmamk_f32 v20, v20, 0x3a800000, v136
	v_mul_f32_e32 v21, 0x4b800000, v20
	v_cmp_gt_f32_e32 vcc, s85, v20
	s_nop 1
	v_cndmask_b32_e32 v20, v20, v21, vcc
	v_rsq_f32_e32 v20, v20
	s_nop 0
	v_mul_f32_e32 v21, 0x45800000, v20
	v_cndmask_b32_e32 v20, v20, v21, vcc
	v_pk_mul_f32 v[4:5], v[4:5], v[20:21] op_sel_hi:[1,0]
	v_pk_mul_f32 v[6:7], v[6:7], v[20:21] op_sel_hi:[1,0]
	v_pk_mul_f32 v[8:9], v[8:9], v[20:21] op_sel_hi:[1,0]
	v_pk_mul_f32 v[10:11], v[10:11], v[20:21] op_sel_hi:[1,0]
	v_pk_mul_f32 v[0:1], v[0:1], v[20:21] op_sel_hi:[1,0]
	v_pk_mul_f32 v[2:3], v[2:3], v[20:21] op_sel_hi:[1,0]
	v_cmp_lt_i32_e32 vcc, s83, v48
	s_or_b64 s[6:7], vcc, s[6:7]
	s_waitcnt vmcnt(0)
	v_pk_mul_f32 v[4:5], v[16:17], v[4:5]
	v_pk_mul_f32 v[6:7], v[18:19], v[6:7]
	v_cvt_pk_bf16_f32 v4, v4, v5
	v_cvt_pk_bf16_f32 v5, v6, v7
	global_store_dwordx2 v[72:73], v[4:5], off offset:2048
	global_load_dwordx4 v[4:7], v[60:61], off
	s_waitcnt vmcnt(0)
	v_pk_mul_f32 v[4:5], v[4:5], v[8:9]
	v_pk_mul_f32 v[6:7], v[6:7], v[10:11]
	v_cvt_pk_bf16_f32 v4, v4, v5
	v_cvt_pk_bf16_f32 v5, v6, v7
	global_store_dwordx2 v[72:73], v[4:5], off offset:2560
	global_load_dwordx4 v[4:7], v[62:63], off
	v_pk_mul_f32 v[8:9], v[12:13], v[20:21] op_sel_hi:[1,0]
	v_pk_mul_f32 v[10:11], v[14:15], v[20:21] op_sel_hi:[1,0]
	s_waitcnt vmcnt(0)
	v_pk_mul_f32 v[4:5], v[8:9], v[4:5]
	v_pk_mul_f32 v[6:7], v[10:11], v[6:7]
	v_cvt_pk_bf16_f32 v4, v4, v5
	v_cvt_pk_bf16_f32 v5, v6, v7
	global_store_dwordx2 v[72:73], v[4:5], off offset:3072
	global_load_dwordx4 v[4:7], v[64:65], off
	s_waitcnt vmcnt(0)
	v_pk_mul_f32 v[0:1], v[0:1], v[4:5]
	v_pk_mul_f32 v[2:3], v[2:3], v[6:7]
	v_cvt_pk_bf16_f32 v0, v0, v1
	v_cvt_pk_bf16_f32 v1, v2, v3
	global_store_dwordx2 v[72:73], v[0:1], off offset:3584
	s_andn2_b64 exec, exec, s[6:7]
	s_cbranch_execnz .LBB0_231

; __device__ __forceinline__ void unpack4(uint2 u, float* f) { f[0] = bflo(u.x); f[1] = bfhi(u.x); f[2] = bflo(u.y); f[3] = bfhi(u.y); }
; __device__ __forceinline__ void resid_norm(const float* hin, const u16* y, const float* gpost, const float* gpre, float* hout, u16* hn,
;                            int job0w, int jstridew) {
;     ...
;   for (int r0 = job0w * RN_R; r0 < T_TOK; r0 += jstridew * RN_R) {
;     uint2 yu[RN_R][4];
;     float4 h4[RN_R][4];
; #pragma unroll
;     for (int q = 0; q < RN_R; q++)
; #pragma unroll
;       for (int i = 0; i < 4; i++) {
;         { typedef unsigned u32x2_ __attribute__((ext_vector_type(2)));
;           const u32x2_ t_ = __builtin_nontemporal_load((const u32x2_*)(y + (size_t)(r0 + q) * 1024 + (lane + i * 64) * 4));
;           yu[q][i] = make_uint2(t_[0], t_[1]); }
;         {
;           const f32x4 t_ = __builtin_nontemporal_load((const f32x4*)(hin + (size_t)(r0 + q) * 1024) + lane + i * 64);
;           h4[q][i] = make_float4(t_[0], t_[1], t_[2], t_[3]); }
;       }
;     float4 gp[4];
; #pragma unroll
;     for (int i = 0; i < 4; i++) gp[i] = ((const float4*)gpost)[lane + i * 64];
; #pragma unroll
;     for (int q = 0; q < RN_R; q++) {
;       const int r = r0 + q;
;       float yv[16];
;       float ss = 0.f;
; #pragma unroll
;       for (int i = 0; i < 4; i++) {
;         unpack4(yu[q][i], yv + i * 4);
; #pragma unroll
;         for (int e = 0; e < 4; e++) ss += yv[i * 4 + e] * yv[i * 4 + e];
;       }
;       ss = wave_sum(ss);
;       const float sc = rsqrtf(ss * (1.f / 1024.f) + 1e-6f);
;       float hv[16];
;       float s2 = 0.f;
; #pragma unroll
;       for (int i = 0; i < 4; i++) {
;         hv[i * 4 + 0] = h4[q][i].x + yv[i * 4 + 0] * sc * gp[i].x;
;         hv[i * 4 + 1] = h4[q][i].y + yv[i * 4 + 1] * sc * gp[i].y;
;         hv[i * 4 + 2] = h4[q][i].z + yv[i * 4 + 2] * sc * gp[i].z;
;         hv[i * 4 + 3] = h4[q][i].w + yv[i * 4 + 3] * sc * gp[i].w;
; #pragma unroll
;         for (int e = 0; e < 4; e++) s2 += hv[i * 4 + e] * hv[i * 4 + e];
;         __builtin_nontemporal_store((f32x4){hv[i * 4], hv[i * 4 + 1], hv[i * 4 + 2], hv[i * 4 + 3]}, (f32x4*)(hout + (size_t)r * 1024) + lane + i * 64);
;       }
.LBB0_309:
	v_lshl_add_u64 v[2:3], v[78:79], 0, v[74:75]
	v_lshl_add_u64 v[0:1], v[70:71], 0, v[134:135]
	global_load_dwordx2 v[12:13], v[2:3], off
	global_load_dwordx4 v[32:35], v[0:1], off nt
	global_load_dwordx2 v[20:21], v[2:3], off offset:512
	global_load_dwordx4 v[36:39], v[0:1], off offset:1024 nt
	global_load_dwordx2 v[22:23], v[2:3], off offset:1024
	global_load_dwordx4 v[48:51], v[0:1], off offset:2048 nt
	global_load_dwordx2 v[40:41], v[2:3], off offset:1536
	global_load_dwordx4 v[82:85], v[0:1], off offset:3072 nt
	global_load_dwordx2 v[94:95], v[2:3], off offset:2048
	v_add_co_u32_e32 v0, vcc, s35, v0
	v_lshl_add_u64 v[80:81], v[72:73], 0, v[134:135]
	s_nop 0
	v_addc_co_u32_e32 v1, vcc, 0, v1, vcc
	global_load_dwordx4 v[16:19], v[0:1], off nt
	global_load_dwordx2 v[92:93], v[2:3], off offset:2560
	global_load_dwordx4 v[8:11], v[0:1], off offset:1024 nt
	global_load_dwordx2 v[90:91], v[2:3], off offset:3072
	global_load_dwordx4 v[4:7], v[0:1], off offset:2048 nt
	global_load_dwordx2 v[88:89], v[2:3], off offset:3584
	s_nop 0
	global_load_dwordx4 v[0:3], v[0:1], off offset:3072 nt
	v_add_u32_e32 v52, s34, v52
	global_load_dwordx4 v[28:31], v[54:55], off
	global_load_dwordx4 v[24:27], v[58:59], off
	v_lshl_add_u64 v[70:71], v[70:71], 0, s[14:15]
	v_lshl_add_u64 v[72:73], v[72:73], 0, s[14:15]
	v_lshl_add_u64 v[78:79], v[78:79], 0, s[16:17]
	s_waitcnt vmcnt(17)
	v_lshlrev_b32_e32 v42, 16, v12
	v_and_b32_e32 v43, 0xffff0000, v12
	v_lshlrev_b32_e32 v46, 16, v13
	v_and_b32_e32 v47, 0xffff0000, v13
	global_load_dwordx4 v[12:15], v[56:57], off
	s_waitcnt vmcnt(16)
	v_lshlrev_b32_e32 v96, 16, v20
	v_and_b32_e32 v97, 0xffff0000, v20
	v_lshlrev_b32_e32 v100, 16, v21
	v_and_b32_e32 v101, 0xffff0000, v21
	s_waitcnt vmcnt(14)
	v_lshlrev_b32_e32 v104, 16, v22
	v_and_b32_e32 v105, 0xffff0000, v22
	v_lshlrev_b32_e32 v108, 16, v23
	v_and_b32_e32 v109, 0xffff0000, v23
	global_load_dwordx4 v[20:23], v[60:61], off
	v_pk_mul_f32 v[44:45], v[42:43], v[42:43]
	v_pk_mul_f32 v[86:87], v[46:47], v[46:47]
	v_add_f32_e32 v44, v44, v45
	v_add_f32_e32 v44, v86, v44
	v_pk_mul_f32 v[98:99], v[96:97], v[96:97]
	v_add_f32_e32 v44, v87, v44
	v_add_f32_e32 v44, v98, v44
	v_pk_mul_f32 v[102:103], v[100:101], v[100:101]
	v_add_f32_e32 v44, v99, v44
	v_add_f32_e32 v44, v102, v44
	v_pk_mul_f32 v[106:107], v[104:105], v[104:105]
	v_add_f32_e32 v44, v103, v44
	v_add_f32_e32 v44, v106, v44
	v_pk_mul_f32 v[110:111], v[108:109], v[108:109]
	v_add_f32_e32 v44, v107, v44
	s_waitcnt vmcnt(13)
	v_lshlrev_b32_e32 v112, 16, v40
	v_and_b32_e32 v113, 0xffff0000, v40
	v_add_f32_e32 v44, v110, v44
	v_pk_mul_f32 v[114:115], v[112:113], v[112:113]
	v_add_f32_e32 v44, v111, v44
	v_lshlrev_b32_e32 v116, 16, v41
	v_and_b32_e32 v117, 0xffff0000, v41
	v_add_f32_e32 v44, v114, v44
	v_pk_mul_f32 v[40:41], v[116:117], v[116:117]
	v_add_f32_e32 v44, v115, v44
	v_add_f32_e32 v40, v40, v44
	v_add_f32_e32 v40, v41, v40
	s_waitcnt vmcnt(11)
	v_lshlrev_b32_e32 v102, 16, v95
	v_and_b32_e32 v103, 0xffff0000, v95
	v_add_f32_dpp v40, v40, v40 quad_perm:[1,0,3,2] row_mask:0xf bank_mask:0xf bound_ctrl:1
	v_pk_mul_f32 v[106:107], v[102:103], v[102:103]
	s_waitcnt vmcnt(9)
	v_and_b32_e32 v95, 0xffff0000, v92
	v_add_f32_dpp v40, v40, v40 quad_perm:[2,3,0,1] row_mask:0xf bank_mask:0xf bound_ctrl:1
	s_nop 1
	v_add_f32_dpp v40, v40, v40 row_half_mirror row_mask:0xf bank_mask:0xf bound_ctrl:1
	s_nop 1
	v_add_f32_dpp v40, v40, v40 row_mirror row_mask:0xf bank_mask:0xf bound_ctrl:1
	v_mov_b32_e32 v41, v40
	s_nop 1
	v_permlane16_swap_b32_e32 v40, v41
	v_add_f32_e32 v40, v40, v41
	v_mov_b32_e32 v41, v40
	s_nop 1
	v_permlane32_swap_b32_e32 v40, v41
	v_add_f32_e32 v40, v40, v41
	v_fmamk_f32 v40, v40, 0x3a800000, v136
	v_cmp_gt_f32_e32 vcc, s85, v40
	v_mul_f32_e32 v41, 0x4b800000, v40
	s_nop 0
	v_cndmask_b32_e32 v40, v40, v41, vcc
	v_rsq_f32_e32 v40, v40
	s_nop 0
	v_mul_f32_e32 v41, 0x45800000, v40
	v_cndmask_b32_e32 v86, v40, v41, vcc
	v_pk_mul_f32 v[40:41], v[86:87], v[42:43] op_sel_hi:[0,1]
	s_waitcnt vmcnt(3)
	v_pk_fma_f32 v[44:45], v[28:29], v[40:41], v[32:33]
	v_pk_mul_f32 v[32:33], v[86:87], v[46:47] op_sel_hi:[0,1]
	v_pk_fma_f32 v[46:47], v[30:31], v[32:33], v[34:35]
	v_pk_mul_f32 v[32:33], v[86:87], v[96:97] op_sel_hi:[0,1]
	v_pk_mul_f32 v[34:35], v[86:87], v[116:117] op_sel_hi:[0,1]
	global_store_dwordx4 v[80:81], v[44:47], off nt
	s_waitcnt vmcnt(2)
	v_pk_fma_f32 v[40:41], v[12:13], v[32:33], v[36:37]
	v_pk_mul_f32 v[32:33], v[86:87], v[100:101] op_sel_hi:[0,1]
	v_pk_fma_f32 v[42:43], v[14:15], v[32:33], v[38:39]
	v_pk_mul_f32 v[32:33], v[86:87], v[104:105] op_sel_hi:[0,1]
	v_pk_fma_f32 v[36:37], v[24:25], v[32:33], v[48:49]
	v_pk_mul_f32 v[32:33], v[86:87], v[108:109] op_sel_hi:[0,1]
	v_pk_mul_f32 v[48:49], v[44:45], v[44:45]
	v_pk_fma_f32 v[38:39], v[26:27], v[32:33], v[50:51]
	v_pk_mul_f32 v[50:51], v[46:47], v[46:47]
	v_add_f32_e32 v48, v48, v49
	v_pk_mul_f32 v[32:33], v[86:87], v[112:113] op_sel_hi:[0,1]
	v_add_f32_e32 v48, v50, v48
	s_waitcnt vmcnt(1)
; __device__ __forceinline__ uint2 pack4(float a, float b, float c, float d) { return make_uint2(pack2(a, b), pack2(c, d)); }
; __device__ __forceinline__ void resid_norm(const float* hin, const u16* y, const float* gpost, const float* gpre, float* hout, u16* hn,
;                            int job0w, int jstridew) {
;     ...
;       ss = wave_sum(ss);
;       const float sc = rsqrtf(ss * (1.f / 1024.f) + 1e-6f);
;       float hv[16];
;       float s2 = 0.f;
; #pragma unroll
;       for (int i = 0; i < 4; i++) {
;         hv[i * 4 + 0] = h4[q][i].x + yv[i * 4 + 0] * sc * gp[i].x;
;         hv[i * 4 + 1] = h4[q][i].y + yv[i * 4 + 1] * sc * gp[i].y;
;         hv[i * 4 + 2] = h4[q][i].z + yv[i * 4 + 2] * sc * gp[i].z;
;         hv[i * 4 + 3] = h4[q][i].w + yv[i * 4 + 3] * sc * gp[i].w;
; #pragma unroll
;         for (int e = 0; e < 4; e++) s2 += hv[i * 4 + e] * hv[i * 4 + e];
;         __builtin_nontemporal_store((f32x4){hv[i * 4], hv[i * 4 + 1], hv[i * 4 + 2], hv[i * 4 + 3]}, (f32x4*)(hout + (size_t)r * 1024) + lane + i * 64);
;       }
;       if (gpre) {
;         s2 = wave_sum(s2);
;         const float sc2 = rsqrtf(s2 * (1.f / 1024.f) + 1e-6f);
; #pragma unroll
;         for (int i = 0; i < 4; i++) {
;           float4 g = ((const float4*)gpre)[lane + i * 64];
;           *(uint2*)(hn + (size_t)r * 1024 + (lane + i * 64) * 4) =
;               pack4(hv[i * 4] * sc2 * g.x, hv[i * 4 + 1] * sc2 * g.y, hv[i * 4 + 2] * sc2 * g.z, hv[i * 4 + 3] * sc2 * g.w);
;         }
	v_pk_fma_f32 v[32:33], v[20:21], v[32:33], v[82:83]
	v_pk_mul_f32 v[82:83], v[40:41], v[40:41]
	v_add_f32_e32 v48, v51, v48
	v_add_f32_e32 v48, v82, v48
	v_pk_fma_f32 v[34:35], v[22:23], v[34:35], v[84:85]
	v_pk_mul_f32 v[84:85], v[42:43], v[42:43]
	v_add_f32_e32 v48, v83, v48
	v_add_f32_e32 v48, v84, v48
	v_pk_mul_f32 v[86:87], v[36:37], v[36:37]
	v_add_f32_e32 v48, v85, v48
	v_add_f32_e32 v48, v86, v48
	v_pk_mul_f32 v[96:97], v[38:39], v[38:39]
	v_add_f32_e32 v48, v87, v48
	v_add_f32_e32 v48, v96, v48
	v_pk_mul_f32 v[98:99], v[32:33], v[32:33]
	v_add_f32_e32 v48, v97, v48
	v_add_f32_e32 v48, v98, v48
	v_pk_mul_f32 v[100:101], v[34:35], v[34:35]
	v_add_f32_e32 v48, v99, v48
	v_add_f32_e32 v48, v100, v48
	v_add_f32_e32 v48, v101, v48
	global_store_dwordx4 v[80:81], v[40:43], off offset:1024 nt
	global_store_dwordx4 v[80:81], v[36:39], off offset:2048 nt
	v_add_f32_dpp v48, v48, v48 quad_perm:[1,0,3,2] row_mask:0xf bank_mask:0xf bound_ctrl:1
	global_store_dwordx4 v[80:81], v[32:35], off offset:3072 nt
	v_lshlrev_b32_e32 v100, 16, v94
	v_add_f32_dpp v48, v48, v48 quad_perm:[2,3,0,1] row_mask:0xf bank_mask:0xf bound_ctrl:1
	v_and_b32_e32 v101, 0xffff0000, v94
	v_pk_mul_f32 v[104:105], v[100:101], v[100:101]
	v_add_f32_dpp v48, v48, v48 row_half_mirror row_mask:0xf bank_mask:0xf bound_ctrl:1
	v_add_f32_e32 v53, v104, v105
	v_lshlrev_b32_e32 v94, 16, v92
	v_add_f32_dpp v48, v48, v48 row_mirror row_mask:0xf bank_mask:0xf bound_ctrl:1
	v_mov_b32_e32 v49, v48
	s_nop 1
	v_permlane16_swap_b32_e32 v48, v49
	v_add_f32_e32 v85, v48, v49
	global_load_dwordx4 v[48:51], v[62:63], off
	v_add_f32_e32 v53, v106, v53
	v_pk_mul_f32 v[108:109], v[94:95], v[94:95]
	v_add_f32_e32 v53, v107, v53
	v_lshlrev_b32_e32 v98, 16, v93
	v_and_b32_e32 v99, 0xffff0000, v93
	v_add_f32_e32 v53, v108, v53
	v_pk_mul_f32 v[110:111], v[98:99], v[98:99]
	v_add_f32_e32 v53, v109, v53
	v_lshlrev_b32_e32 v92, 16, v90
	v_and_b32_e32 v93, 0xffff0000, v90
	v_add_f32_e32 v53, v110, v53
	v_pk_mul_f32 v[112:113], v[92:93], v[92:93]
	v_add_f32_e32 v53, v111, v53
	v_lshlrev_b32_e32 v96, 16, v91
	v_and_b32_e32 v97, 0xffff0000, v91
	v_add_f32_e32 v53, v112, v53
	v_pk_mul_f32 v[114:115], v[96:97], v[96:97]
	v_add_f32_e32 v53, v113, v53
	v_lshlrev_b32_e32 v90, 16, v88
	v_and_b32_e32 v91, 0xffff0000, v88
	v_add_f32_e32 v53, v114, v53
	v_pk_mul_f32 v[116:117], v[90:91], v[90:91]
	v_add_f32_e32 v53, v115, v53
	v_lshlrev_b32_e32 v88, 16, v89
	v_and_b32_e32 v89, 0xffff0000, v89
	v_add_f32_e32 v53, v116, v53
	v_pk_mul_f32 v[118:119], v[88:89], v[88:89]
	v_add_f32_e32 v53, v117, v53
	v_add_f32_e32 v53, v118, v53
	v_add_f32_e32 v53, v119, v53
	v_mov_b32_e32 v87, v85
	s_nop 1
	v_permlane32_swap_b32_e32 v85, v87
	v_add_f32_dpp v53, v53, v53 quad_perm:[1,0,3,2] row_mask:0xf bank_mask:0xf bound_ctrl:1
	v_lshl_add_u64 v[82:83], v[76:77], 0, v[74:75]
	v_lshl_add_u64 v[76:77], v[76:77], 0, s[16:17]
	v_add_f32_dpp v53, v53, v53 quad_perm:[2,3,0,1] row_mask:0xf bank_mask:0xf bound_ctrl:1
	s_nop 1
	v_add_f32_dpp v53, v53, v53 row_half_mirror row_mask:0xf bank_mask:0xf bound_ctrl:1
	s_nop 1
	v_add_f32_dpp v53, v53, v53 row_mirror row_mask:0xf bank_mask:0xf bound_ctrl:1
	v_mov_b32_e32 v84, v53
	s_nop 1
	v_permlane16_swap_b32_e32 v53, v84
	v_add_f32_e32 v84, v53, v84
	v_mov_b32_e32 v86, v84
	s_nop 1
	v_permlane32_swap_b32_e32 v84, v86
	v_pk_add_f32 v[84:85], v[84:85], v[86:87]
	s_nop 0
	v_pk_fma_f32 v[84:85], v[84:85], s[4:5], v[136:137] op_sel_hi:[1,0,0]
	s_nop 0
	v_mul_f32_e32 v53, 0x4b800000, v85
	v_cmp_gt_f32_e64 s[6:7], s85, v85
	v_cmp_gt_f32_e32 vcc, s85, v84
	s_nop 0
	v_cndmask_b32_e64 v53, v85, v53, s[6:7]
	v_rsq_f32_e32 v53, v53
	s_nop 0
	v_mul_f32_e32 v85, 0x45800000, v53
	v_cndmask_b32_e64 v86, v53, v85, s[6:7]
	v_pk_mul_f32 v[44:45], v[44:45], v[86:87] op_sel_hi:[1,0]
	v_pk_mul_f32 v[46:47], v[46:47], v[86:87] op_sel_hi:[1,0]
	v_pk_mul_f32 v[40:41], v[40:41], v[86:87] op_sel_hi:[1,0]
	v_pk_mul_f32 v[42:43], v[42:43], v[86:87] op_sel_hi:[1,0]
	v_pk_mul_f32 v[36:37], v[36:37], v[86:87] op_sel_hi:[1,0]
	v_pk_mul_f32 v[38:39], v[38:39], v[86:87] op_sel_hi:[1,0]
	v_pk_mul_f32 v[32:33], v[32:33], v[86:87] op_sel_hi:[1,0]
	v_pk_mul_f32 v[34:35], v[34:35], v[86:87] op_sel_hi:[1,0]
	s_waitcnt vmcnt(0)
	v_pk_mul_f32 v[44:45], v[48:49], v[44:45]
	v_pk_mul_f32 v[46:47], v[50:51], v[46:47]
	v_cvt_pk_bf16_f32 v44, v44, v45
	v_cvt_pk_bf16_f32 v45, v46, v47
	global_store_dwordx2 v[82:83], v[44:45], off
	global_load_dwordx4 v[44:47], v[64:65], off
	s_waitcnt vmcnt(0)
	v_pk_mul_f32 v[40:41], v[44:45], v[40:41]
	v_pk_mul_f32 v[42:43], v[46:47], v[42:43]
	v_cvt_pk_bf16_f32 v40, v40, v41
	v_cvt_pk_bf16_f32 v41, v42, v43
	global_store_dwordx2 v[82:83], v[40:41], off offset:512
	global_load_dwordx4 v[40:43], v[66:67], off
	s_waitcnt vmcnt(0)
	v_pk_mul_f32 v[36:37], v[36:37], v[40:41]
	v_pk_mul_f32 v[38:39], v[38:39], v[42:43]
	v_cvt_pk_bf16_f32 v36, v36, v37
	v_cvt_pk_bf16_f32 v37, v38, v39
	global_store_dwordx2 v[82:83], v[36:37], off offset:1024
	global_load_dwordx4 v[36:39], v[68:69], off
	s_waitcnt vmcnt(0)
; __device__ __forceinline__ uint2 pack4(float a, float b, float c, float d) { return make_uint2(pack2(a, b), pack2(c, d)); }
; __device__ __forceinline__ void resid_norm(const float* hin, const u16* y, const float* gpost, const float* gpre, float* hout, u16* hn,
;                            int job0w, int jstridew) {
;     ...
;       ss = wave_sum(ss);
;       const float sc = rsqrtf(ss * (1.f / 1024.f) + 1e-6f);
;       float hv[16];
;       float s2 = 0.f;
; #pragma unroll
;       for (int i = 0; i < 4; i++) {
;         hv[i * 4 + 0] = h4[q][i].x + yv[i * 4 + 0] * sc * gp[i].x;
;         hv[i * 4 + 1] = h4[q][i].y + yv[i * 4 + 1] * sc * gp[i].y;
;         hv[i * 4 + 2] = h4[q][i].z + yv[i * 4 + 2] * sc * gp[i].z;
;         hv[i * 4 + 3] = h4[q][i].w + yv[i * 4 + 3] * sc * gp[i].w;
; #pragma unroll
;         for (int e = 0; e < 4; e++) s2 += hv[i * 4 + e] * hv[i * 4 + e];
;         __builtin_nontemporal_store((f32x4){hv[i * 4], hv[i * 4 + 1], hv[i * 4 + 2], hv[i * 4 + 3]}, (f32x4*)(hout + (size_t)r * 1024) + lane + i * 64);
;       }
;       if (gpre) {
;         s2 = wave_sum(s2);
;         const float sc2 = rsqrtf(s2 * (1.f / 1024.f) + 1e-6f);
; #pragma unroll
;         for (int i = 0; i < 4; i++) {
;           float4 g = ((const float4*)gpre)[lane + i * 64];
;           *(uint2*)(hn + (size_t)r * 1024 + (lane + i * 64) * 4) =
;               pack4(hv[i * 4] * sc2 * g.x, hv[i * 4 + 1] * sc2 * g.y, hv[i * 4 + 2] * sc2 * g.z, hv[i * 4 + 3] * sc2 * g.w);
;         }
	v_pk_mul_f32 v[32:33], v[32:33], v[36:37]
	v_pk_mul_f32 v[34:35], v[34:35], v[38:39]
	v_cvt_pk_bf16_f32 v32, v32, v33
	v_cvt_pk_bf16_f32 v33, v34, v35
	global_store_dwordx2 v[82:83], v[32:33], off offset:1536
	v_mul_f32_e32 v32, 0x4b800000, v84
	v_cndmask_b32_e32 v32, v84, v32, vcc
	v_rsq_f32_e32 v32, v32
	s_nop 0
	v_mul_f32_e32 v33, 0x45800000, v32
	v_cndmask_b32_e32 v32, v32, v33, vcc
	v_pk_mul_f32 v[34:35], v[32:33], v[100:101] op_sel_hi:[0,1]
	v_pk_fma_f32 v[16:17], v[28:29], v[34:35], v[16:17]
	v_pk_mul_f32 v[28:29], v[32:33], v[102:103] op_sel_hi:[0,1]
	v_pk_fma_f32 v[18:19], v[30:31], v[28:29], v[18:19]
	v_pk_mul_f32 v[30:31], v[32:33], v[94:95] op_sel_hi:[0,1]
	v_pk_fma_f32 v[8:9], v[12:13], v[30:31], v[8:9]
	v_pk_mul_f32 v[12:13], v[32:33], v[98:99] op_sel_hi:[0,1]
	v_pk_fma_f32 v[10:11], v[14:15], v[12:13], v[10:11]
	v_pk_mul_f32 v[12:13], v[32:33], v[92:93] op_sel_hi:[0,1]
	v_pk_fma_f32 v[4:5], v[24:25], v[12:13], v[4:5]
	v_pk_mul_f32 v[12:13], v[32:33], v[96:97] op_sel_hi:[0,1]
	v_pk_fma_f32 v[6:7], v[26:27], v[12:13], v[6:7]
	v_pk_mul_f32 v[12:13], v[32:33], v[90:91] op_sel_hi:[0,1]
	v_pk_fma_f32 v[0:1], v[20:21], v[12:13], v[0:1]
	v_pk_mul_f32 v[12:13], v[32:33], v[88:89] op_sel_hi:[0,1]
	v_pk_fma_f32 v[2:3], v[22:23], v[12:13], v[2:3]
	v_pk_mul_f32 v[12:13], v[16:17], v[16:17]
	v_pk_mul_f32 v[14:15], v[18:19], v[18:19]
	v_add_f32_e32 v12, v12, v13
	v_add_f32_e32 v12, v14, v12
	v_pk_mul_f32 v[20:21], v[8:9], v[8:9]
	v_add_f32_e32 v12, v15, v12
	v_add_co_u32_e32 v28, vcc, s35, v80
	v_add_f32_e32 v12, v20, v12
	s_nop 0
	v_addc_co_u32_e32 v29, vcc, 0, v81, vcc
	v_pk_mul_f32 v[22:23], v[10:11], v[10:11]
	v_add_f32_e32 v12, v21, v12
	global_store_dwordx4 v[28:29], v[16:19], off nt
	global_store_dwordx4 v[28:29], v[8:11], off offset:1024 nt
	global_store_dwordx4 v[28:29], v[4:7], off offset:2048 nt
	global_store_dwordx4 v[28:29], v[0:3], off offset:3072 nt
	v_add_f32_e32 v12, v22, v12
	v_add_f32_e32 v12, v23, v12
	global_load_dwordx4 v[20:23], v[62:63], off
	v_pk_mul_f32 v[24:25], v[4:5], v[4:5]
	v_pk_mul_f32 v[26:27], v[6:7], v[6:7]
	v_add_f32_e32 v12, v24, v12
	v_add_f32_e32 v12, v25, v12
	v_add_f32_e32 v12, v26, v12
	v_pk_mul_f32 v[28:29], v[0:1], v[0:1]
	v_add_f32_e32 v12, v27, v12
	v_add_f32_e32 v12, v28, v12
	v_pk_mul_f32 v[30:31], v[2:3], v[2:3]
	v_add_f32_e32 v12, v29, v12
	v_add_f32_e32 v12, v30, v12
	v_add_f32_e32 v12, v31, v12
	s_nop 1
	v_add_f32_dpp v12, v12, v12 quad_perm:[1,0,3,2] row_mask:0xf bank_mask:0xf bound_ctrl:1
	s_nop 1
	v_add_f32_dpp v12, v12, v12 quad_perm:[2,3,0,1] row_mask:0xf bank_mask:0xf bound_ctrl:1
	s_nop 1
	v_add_f32_dpp v12, v12, v12 row_half_mirror row_mask:0xf bank_mask:0xf bound_ctrl:1
	s_nop 1
	v_add_f32_dpp v12, v12, v12 row_mirror row_mask:0xf bank_mask:0xf bound_ctrl:1
	v_mov_b32_e32 v13, v12
	s_nop 1
	v_permlane16_swap_b32_e32 v12, v13
	v_add_f32_e32 v12, v12, v13
	v_mov_b32_e32 v13, v12
	s_nop 1
	v_permlane32_swap_b32_e32 v12, v13
	v_add_f32_e32 v12, v12, v13
	v_fmamk_f32 v12, v12, 0x3a800000, v136
	v_cmp_gt_f32_e32 vcc, s85, v12
	v_mul_f32_e32 v13, 0x4b800000, v12
	s_nop 0
	v_cndmask_b32_e32 v12, v12, v13, vcc
	v_rsq_f32_e32 v12, v12
	s_nop 0
	v_mul_f32_e32 v13, 0x45800000, v12
	v_cndmask_b32_e32 v12, v12, v13, vcc
	v_pk_mul_f32 v[14:15], v[16:17], v[12:13] op_sel_hi:[1,0]
	v_pk_mul_f32 v[16:17], v[18:19], v[12:13] op_sel_hi:[1,0]
	v_pk_mul_f32 v[8:9], v[8:9], v[12:13] op_sel_hi:[1,0]
	v_pk_mul_f32 v[10:11], v[10:11], v[12:13] op_sel_hi:[1,0]
	v_pk_mul_f32 v[4:5], v[4:5], v[12:13] op_sel_hi:[1,0]
	v_pk_mul_f32 v[6:7], v[6:7], v[12:13] op_sel_hi:[1,0]
	v_pk_mul_f32 v[0:1], v[0:1], v[12:13] op_sel_hi:[1,0]
	v_pk_mul_f32 v[2:3], v[2:3], v[12:13] op_sel_hi:[1,0]
	v_cmp_lt_i32_e32 vcc, s83, v52
	s_or_b64 s[10:11], vcc, s[10:11]
	s_waitcnt vmcnt(0)
	v_pk_mul_f32 v[14:15], v[20:21], v[14:15]
	v_pk_mul_f32 v[16:17], v[22:23], v[16:17]
	v_cvt_pk_bf16_f32 v14, v14, v15
	v_cvt_pk_bf16_f32 v15, v16, v17
	global_store_dwordx2 v[82:83], v[14:15], off offset:2048
	global_load_dwordx4 v[14:17], v[64:65], off
	s_waitcnt vmcnt(0)
	v_pk_mul_f32 v[8:9], v[14:15], v[8:9]
	v_pk_mul_f32 v[10:11], v[16:17], v[10:11]
	v_cvt_pk_bf16_f32 v8, v8, v9
	v_cvt_pk_bf16_f32 v9, v10, v11
	global_store_dwordx2 v[82:83], v[8:9], off offset:2560
	global_load_dwordx4 v[8:11], v[66:67], off
	s_waitcnt vmcnt(0)
	v_pk_mul_f32 v[4:5], v[4:5], v[8:9]
	v_pk_mul_f32 v[6:7], v[6:7], v[10:11]
	v_cvt_pk_bf16_f32 v4, v4, v5
	v_cvt_pk_bf16_f32 v5, v6, v7
	global_store_dwordx2 v[82:83], v[4:5], off offset:3072
	global_load_dwordx4 v[4:7], v[68:69], off
	s_waitcnt vmcnt(0)
	v_pk_mul_f32 v[0:1], v[0:1], v[4:5]
	v_pk_mul_f32 v[2:3], v[2:3], v[6:7]
	v_cvt_pk_bf16_f32 v0, v0, v1
	v_cvt_pk_bf16_f32 v1, v2, v3
	global_store_dwordx2 v[82:83], v[0:1], off offset:3584
	s_andn2_b64 exec, exec, s[10:11]
	s_cbranch_execnz .LBB0_309
